# kinner MFMA order + LDS-DMA loads in SGPR-base form (no 64-bit VALU address adds in the K-loop)
# speedup vs baseline: 1.0051x; 1.0051x over previous
; #define PG8_STAGE(bufoff, gbase, voff) do { _Pragma("unroll") for (int _i = 0; _i < 2; ++_i) \
;         __builtin_amdgcn_global_load_lds((const unsigned*)((const char*)(gbase) + (voff)[_i]), (PG8_LAS unsigned*)(lds + (bufoff) + ldsw + _i * 8192), 16, 0, 0); } while (0)
; #define PG8_LDA(dst, b, h) do { _Pragma("unroll") for (int m = 0; m < 4; ++m) _Pragma("unroll") for (int k = 0; k < 2; ++k) dst[m][k] = *(const PG8_LAS bf16x8*)(lds + PG8_SA(b, h) + aoff + m * 2048 + k * 1024); } while (0)
; #define PG8_LDB(dst, b, h) do { _Pragma("unroll") for (int n = 0; n < 2; ++n) _Pragma("unroll") for (int k = 0; k < 2; ++k) dst[n][k] = *(const PG8_LAS bf16x8*)(lds + PG8_SB(b, h) + boff + n * 2048 + k * 1024); } while (0)
; #define PG8_MMA(ai, bj, At, Bt) do { __builtin_amdgcn_s_setprio(1); _Pragma("unroll") for (int m = 0; m < 4; ++m) _Pragma("unroll") for (int n = 0; n < 2; ++n) _Pragma("unroll") for (int k = 0; k < 2; ++k) \
;         acc[ai][bj][m][n] = __builtin_amdgcn_mfma_f32_16x16x32_bf16(Bt[n][k], At[m][k], acc[ai][bj][m][n], 0, 0, 0); __builtin_amdgcn_s_setprio(0); } while (0)
; #define PG8_WAIT_V(n) asm volatile("s_waitcnt vmcnt(" #n ")" ::: "memory")
; #define PG8_BAR __builtin_amdgcn_s_barrier()
; template <class Epi, class Sched, bool ALIGN_EPI = false, bool SP2 = false>
; __device__ __forceinline__ void gemm_phase(PG8_LAS unsigned char* lds, const Gemm g, const Sched& S, const Epi& E) {
;     ...
;         for (int t = 0; t < nt; t += 2) {
;             const bool last = (t == nt - 2);
;             const char* a1 = cA + (size_t)(t + 1) * kstep;
;             const char* a2 = last ? nA : cA + (size_t)(t + 2) * kstep; const char* b2 = last ? nB : cB + (size_t)(t + 2) * kstep;
;             const char* a3 = a2 + kstep; const char* b3 = b2 + kstep;
;             if (last && has_next) S.a_ready(nxt);
;             if constexpr (SP2) {
;             PG8_LDB(B0, 0, 0); PG8_LDB(B1, 0, 1); PG8_SCHED; PG8_LDA(At, 0, 0); PG8_STAGE(PG8_SA(1, 1), a1 + hstep, voffA);
;             PG8_WAIT_V(8); PG8_WAIT_L(0); PG8_BAR; PG8_MMA(0, 0, At, B0); PG8_MMA(0, 1, At, B1); PG8_BAR; PG8_SCHED;
;             PG8_LDA(At, 0, 1); PG8_STAGE(PG8_SB(0, 0), b2, voffB); PG8_STAGE(PG8_SB(0, 1), b2 + hstep, voffB); PG8_STAGE(PG8_SA(0, 0), a2, voffA);
;             PG8_WAIT_V(8); PG8_WAIT_L(0); PG8_BAR; PG8_MMA(1, 0, At, B0); PG8_MMA(1, 1, At, B1); PG8_BAR; PG8_SCHED;
.LBB0_192:
	ds_read_b128 v[162:165], v158
	ds_read_b128 v[166:169], v158 offset:1024
	ds_read_b128 v[170:173], v158 offset:2048
	ds_read_b128 v[174:177], v158 offset:3072
	ds_read_b128 v[188:191], v159
	ds_read_b128 v[196:199], v159 offset:1024
	ds_read_b128 v[200:203], v159 offset:2048
	ds_read_b128 v[204:207], v159 offset:3072
	s_add_u32 s55, s66, 0xfff80080
	s_addc_u32 s56, s67, -1
	s_cmp_eq_u32 s54, 28
	s_cselect_b32 s71, s19, s56
	s_cselect_b32 s70, s50, s55
	s_cselect_b32 s69, s17, s53
	s_cselect_b32 s68, s51, s52
	s_add_i32 m0, s37, 0xc000
	ds_read_b128 v[208:211], v161
	ds_read_b128 v[212:215], v161 offset:1024
	ds_read_b128 v[216:219], v161 offset:2048
	ds_read_b128 v[220:223], v161 offset:3072
	ds_read_b128 v[224:227], v161 offset:4096
	ds_read_b128 v[228:231], v161 offset:5120
	ds_read_b128 v[232:235], v161 offset:6144
	ds_read_b128 v[236:239], v161 offset:7168
	global_load_lds_dwordx4 v128, s[66:67]
	s_add_i32 m0, s37, 0xe000
	s_nop 0
	global_load_lds_dwordx4 v130, s[66:67]
	s_waitcnt vmcnt(8)
	s_waitcnt lgkmcnt(0)
	s_barrier
	s_setprio 1
	s_waitcnt lgkmcnt(0)
	v_mfma_f32_16x16x32_bf16 v[124:127], v[162:165], v[208:211], v[124:127]
	v_mfma_f32_16x16x32_bf16 v[124:127], v[166:169], v[212:215], v[124:127]
	v_mfma_f32_16x16x32_bf16 v[116:119], v[174:177], v[212:215], v[116:119]
	v_mfma_f32_16x16x32_bf16 v[116:119], v[170:173], v[208:211], v[116:119]
	v_mfma_f32_16x16x32_bf16 v[100:103], v[170:173], v[216:219], v[100:103]
	v_mfma_f32_16x16x32_bf16 v[100:103], v[174:177], v[220:223], v[100:103]
	v_mfma_f32_16x16x32_bf16 v[108:111], v[166:169], v[220:223], v[108:111]
	v_mfma_f32_16x16x32_bf16 v[108:111], v[162:165], v[216:219], v[108:111]
	v_mfma_f32_16x16x32_bf16 v[92:95], v[162:165], v[224:227], v[92:95]
	v_mfma_f32_16x16x32_bf16 v[92:95], v[166:169], v[228:231], v[92:95]
	v_mfma_f32_16x16x32_bf16 v[84:87], v[174:177], v[228:231], v[84:87]
	v_mfma_f32_16x16x32_bf16 v[84:87], v[170:173], v[224:227], v[84:87]
	v_mfma_f32_16x16x32_bf16 v[68:71], v[170:173], v[232:235], v[68:71]
	v_mfma_f32_16x16x32_bf16 v[68:71], v[174:177], v[236:239], v[68:71]
	v_mfma_f32_16x16x32_bf16 v[76:79], v[166:169], v[236:239], v[76:79]
	v_mfma_f32_16x16x32_bf16 v[76:79], v[162:165], v[232:235], v[76:79]
	s_setprio 0
	s_setprio 1
	v_mfma_f32_16x16x32_bf16 v[120:123], v[188:191], v[208:211], v[120:123]
	v_mfma_f32_16x16x32_bf16 v[120:123], v[196:199], v[212:215], v[120:123]
	v_mfma_f32_16x16x32_bf16 v[112:115], v[204:207], v[212:215], v[112:115]
	v_mfma_f32_16x16x32_bf16 v[112:115], v[200:203], v[208:211], v[112:115]
	v_mfma_f32_16x16x32_bf16 v[96:99], v[200:203], v[216:219], v[96:99]
	v_mfma_f32_16x16x32_bf16 v[96:99], v[204:207], v[220:223], v[96:99]
	v_mfma_f32_16x16x32_bf16 v[104:107], v[196:199], v[220:223], v[104:107]
	v_mfma_f32_16x16x32_bf16 v[104:107], v[188:191], v[216:219], v[104:107]
	v_mfma_f32_16x16x32_bf16 v[88:91], v[188:191], v[224:227], v[88:91]
	v_mfma_f32_16x16x32_bf16 v[88:91], v[196:199], v[228:231], v[88:91]
	v_mfma_f32_16x16x32_bf16 v[80:83], v[204:207], v[228:231], v[80:83]
	v_mfma_f32_16x16x32_bf16 v[80:83], v[200:203], v[224:227], v[80:83]
	v_mfma_f32_16x16x32_bf16 v[64:67], v[200:203], v[232:235], v[64:67]
	v_mfma_f32_16x16x32_bf16 v[64:67], v[204:207], v[236:239], v[64:67]
	v_mfma_f32_16x16x32_bf16 v[72:75], v[196:199], v[236:239], v[72:75]
	v_mfma_f32_16x16x32_bf16 v[72:75], v[188:191], v[232:235], v[72:75]
	s_setprio 0
	s_barrier
	s_add_u32 s98, s68, 0x80
	s_addc_u32 s99, s69, 0
	s_add_u32 s100, s70, 0x80
	s_addc_u32 s101, s71, 0
	s_add_i32 s55, s46, s36
	s_mov_b32 m0, s55
	ds_read_b128 v[208:211], v161 offset:16384
	ds_read_b128 v[212:215], v161 offset:17408
	ds_read_b128 v[216:219], v161 offset:18432
	ds_read_b128 v[220:223], v161 offset:19456
	ds_read_b128 v[224:227], v161 offset:20480
	ds_read_b128 v[228:231], v161 offset:21504
	ds_read_b128 v[232:235], v161 offset:22528
	ds_read_b128 v[236:239], v161 offset:23552
	global_load_lds_dwordx4 v152, s[68:69]
	s_add_i32 m0, s55, 0x2000
	s_add_u32 s56, s68, 0x80000
	s_addc_u32 s57, s69, 0
	s_add_i32 s55, s47, s36
	global_load_lds_dwordx4 v156, s[68:69]
	s_mov_b32 m0, s55
	s_nop 0
	global_load_lds_dwordx4 v152, s[56:57]
	s_add_i32 m0, s55, 0x2000
	s_nop 0
	global_load_lds_dwordx4 v156, s[56:57]
	s_mov_b32 m0, s37
	s_nop 0
	global_load_lds_dwordx4 v150, s[70:71]
	s_mov_b32 m0, s38
	s_nop 0
	global_load_lds_dwordx4 v154, s[70:71]
	s_waitcnt vmcnt(8)
	s_waitcnt lgkmcnt(0)
	s_barrier
	s_setprio 1
	s_waitcnt lgkmcnt(0)
	v_mfma_f32_16x16x32_bf16 v[60:63], v[162:165], v[208:211], v[60:63]
	v_mfma_f32_16x16x32_bf16 v[60:63], v[166:169], v[212:215], v[60:63]
	v_mfma_f32_16x16x32_bf16 v[52:55], v[174:177], v[212:215], v[52:55]
	v_mfma_f32_16x16x32_bf16 v[52:55], v[170:173], v[208:211], v[52:55]
	v_mfma_f32_16x16x32_bf16 v[36:39], v[170:173], v[216:219], v[36:39]
	v_mfma_f32_16x16x32_bf16 v[36:39], v[174:177], v[220:223], v[36:39]
	v_mfma_f32_16x16x32_bf16 v[44:47], v[166:169], v[220:223], v[44:47]
	v_mfma_f32_16x16x32_bf16 v[44:47], v[162:165], v[216:219], v[44:47]
	v_mfma_f32_16x16x32_bf16 v[28:31], v[162:165], v[224:227], v[28:31]
	v_mfma_f32_16x16x32_bf16 v[28:31], v[166:169], v[228:231], v[28:31]
	v_mfma_f32_16x16x32_bf16 v[20:23], v[174:177], v[228:231], v[20:23]
	v_mfma_f32_16x16x32_bf16 v[20:23], v[170:173], v[224:227], v[20:23]
	v_mfma_f32_16x16x32_bf16 v[4:7], v[170:173], v[232:235], v[4:7]
	v_mfma_f32_16x16x32_bf16 v[4:7], v[174:177], v[236:239], v[4:7]
	v_mfma_f32_16x16x32_bf16 v[12:15], v[166:169], v[236:239], v[12:15]
	v_mfma_f32_16x16x32_bf16 v[12:15], v[162:165], v[232:235], v[12:15]
	s_setprio 0
	s_setprio 1
	v_mfma_f32_16x16x32_bf16 v[56:59], v[188:191], v[208:211], v[56:59]
	v_mfma_f32_16x16x32_bf16 v[56:59], v[196:199], v[212:215], v[56:59]
	v_mfma_f32_16x16x32_bf16 v[48:51], v[204:207], v[212:215], v[48:51]
	v_mfma_f32_16x16x32_bf16 v[48:51], v[200:203], v[208:211], v[48:51]
	v_mfma_f32_16x16x32_bf16 v[32:35], v[200:203], v[216:219], v[32:35]
	v_mfma_f32_16x16x32_bf16 v[32:35], v[204:207], v[220:223], v[32:35]
	v_mfma_f32_16x16x32_bf16 v[40:43], v[196:199], v[220:223], v[40:43]
	v_mfma_f32_16x16x32_bf16 v[40:43], v[188:191], v[216:219], v[40:43]
	v_mfma_f32_16x16x32_bf16 v[24:27], v[188:191], v[224:227], v[24:27]
	v_mfma_f32_16x16x32_bf16 v[24:27], v[196:199], v[228:231], v[24:27]
	v_mfma_f32_16x16x32_bf16 v[16:19], v[204:207], v[228:231], v[16:19]
	v_mfma_f32_16x16x32_bf16 v[16:19], v[200:203], v[224:227], v[16:19]
	v_mfma_f32_16x16x32_bf16 v[0:3], v[200:203], v[232:235], v[0:3]
	v_mfma_f32_16x16x32_bf16 v[0:3], v[204:207], v[236:239], v[0:3]
	v_mfma_f32_16x16x32_bf16 v[8:11], v[196:199], v[236:239], v[8:11]
	v_mfma_f32_16x16x32_bf16 v[8:11], v[188:191], v[232:235], v[8:11]
	s_setprio 0
	s_barrier
; #define PG8_STAGE(bufoff, gbase, voff) do { _Pragma("unroll") for (int _i = 0; _i < 2; ++_i) \
;         __builtin_amdgcn_global_load_lds((const unsigned*)((const char*)(gbase) + (voff)[_i]), (PG8_LAS unsigned*)(lds + (bufoff) + ldsw + _i * 8192), 16, 0, 0); } while (0)
; #define PG8_LDA(dst, b, h) do { _Pragma("unroll") for (int m = 0; m < 4; ++m) _Pragma("unroll") for (int k = 0; k < 2; ++k) dst[m][k] = *(const PG8_LAS bf16x8*)(lds + PG8_SA(b, h) + aoff + m * 2048 + k * 1024); } while (0)
; #define PG8_LDB(dst, b, h) do { _Pragma("unroll") for (int n = 0; n < 2; ++n) _Pragma("unroll") for (int k = 0; k < 2; ++k) dst[n][k] = *(const PG8_LAS bf16x8*)(lds + PG8_SB(b, h) + boff + n * 2048 + k * 1024); } while (0)
; #define PG8_MMA(ai, bj, At, Bt) do { __builtin_amdgcn_s_setprio(1); _Pragma("unroll") for (int m = 0; m < 4; ++m) _Pragma("unroll") for (int n = 0; n < 2; ++n) _Pragma("unroll") for (int k = 0; k < 2; ++k) \
;         acc[ai][bj][m][n] = __builtin_amdgcn_mfma_f32_16x16x32_bf16(Bt[n][k], At[m][k], acc[ai][bj][m][n], 0, 0, 0); __builtin_amdgcn_s_setprio(0); } while (0)
; #define PG8_WAIT_V(n) asm volatile("s_waitcnt vmcnt(" #n ")" ::: "memory")
; #define PG8_WAIT_L(n) asm volatile("s_waitcnt lgkmcnt(" #n ")" ::: "memory")
; #define PG8_BAR __builtin_amdgcn_s_barrier()
; #define PG8_SCHED __builtin_amdgcn_sched_barrier(0)
; template <class Epi, class Sched, bool ALIGN_EPI = false, bool SP2 = false>
; __device__ __forceinline__ void gemm_phase(PG8_LAS unsigned char* lds, const Gemm g, const Sched& S, const Epi& E) {
;     ...
;             PG8_LDB(B0, 1, 0); PG8_LDB(B1, 1, 1); PG8_SCHED; PG8_LDA(At, 1, 0); PG8_STAGE(PG8_SA(0, 1), a2 + hstep, voffA);
;             PG8_WAIT_V(8); PG8_WAIT_L(0); PG8_BAR; PG8_MMA(0, 0, At, B0); PG8_MMA(0, 1, At, B1); PG8_BAR; PG8_SCHED;
;             PG8_LDA(At, 1, 1); PG8_STAGE(PG8_SB(1, 0), b3, voffB); PG8_STAGE(PG8_SB(1, 1), b3 + hstep, voffB); PG8_STAGE(PG8_SA(1, 0), a3, voffA);
;             PG8_WAIT_V(8); PG8_WAIT_L(0); PG8_BAR; PG8_MMA(1, 0, At, B0); PG8_MMA(1, 1, At, B1); PG8_BAR; PG8_SCHED;
;     ...
;         if constexpr (ALIGN_EPI) { if (wr == 0) PG8_BAR; }
	s_add_i32 s55, 0, 0x18000
	s_add_i32 s58, 0, 0x1c000
	v_add_u32_e32 v174, s55, v148
	v_add_u32_e32 v183, s58, v148
	ds_read_b128 v[162:165], v174
	ds_read_b128 v[166:169], v174 offset:1024
	ds_read_b128 v[170:173], v174 offset:2048
	ds_read_b128 v[174:177], v174 offset:3072
	ds_read_b128 v[188:191], v183
	ds_read_b128 v[196:199], v183 offset:1024
	ds_read_b128 v[200:203], v183 offset:2048
	ds_read_b128 v[204:207], v183 offset:3072
	s_add_u32 s56, s70, 0x80000
	s_addc_u32 s57, s71, 0
	s_mov_b32 m0, s39
	ds_read_b128 v[208:211], v161 offset:32768
	ds_read_b128 v[212:215], v161 offset:33792
	ds_read_b128 v[216:219], v161 offset:34816
	ds_read_b128 v[220:223], v161 offset:35840
	ds_read_b128 v[224:227], v161 offset:36864
	ds_read_b128 v[228:231], v161 offset:37888
	ds_read_b128 v[232:235], v161 offset:38912
	ds_read_b128 v[236:239], v161 offset:39936
	global_load_lds_dwordx4 v150, s[56:57]
	s_mov_b32 m0, s40
	s_nop 0
	global_load_lds_dwordx4 v154, s[56:57]
	s_waitcnt vmcnt(8)
	s_waitcnt lgkmcnt(0)
	s_barrier
	s_setprio 1
	s_waitcnt lgkmcnt(0)
	v_mfma_f32_16x16x32_bf16 v[124:127], v[162:165], v[208:211], v[124:127]
	v_mfma_f32_16x16x32_bf16 v[124:127], v[166:169], v[212:215], v[124:127]
	v_mfma_f32_16x16x32_bf16 v[116:119], v[174:177], v[212:215], v[116:119]
	v_mfma_f32_16x16x32_bf16 v[116:119], v[170:173], v[208:211], v[116:119]
	v_mfma_f32_16x16x32_bf16 v[100:103], v[170:173], v[216:219], v[100:103]
	v_mfma_f32_16x16x32_bf16 v[100:103], v[174:177], v[220:223], v[100:103]
	v_mfma_f32_16x16x32_bf16 v[108:111], v[166:169], v[220:223], v[108:111]
	v_mfma_f32_16x16x32_bf16 v[108:111], v[162:165], v[216:219], v[108:111]
	v_mfma_f32_16x16x32_bf16 v[92:95], v[162:165], v[224:227], v[92:95]
	v_mfma_f32_16x16x32_bf16 v[92:95], v[166:169], v[228:231], v[92:95]
	v_mfma_f32_16x16x32_bf16 v[84:87], v[174:177], v[228:231], v[84:87]
	v_mfma_f32_16x16x32_bf16 v[84:87], v[170:173], v[224:227], v[84:87]
	v_mfma_f32_16x16x32_bf16 v[68:71], v[170:173], v[232:235], v[68:71]
	v_mfma_f32_16x16x32_bf16 v[68:71], v[174:177], v[236:239], v[68:71]
	v_mfma_f32_16x16x32_bf16 v[76:79], v[166:169], v[236:239], v[76:79]
	v_mfma_f32_16x16x32_bf16 v[76:79], v[162:165], v[232:235], v[76:79]
	s_setprio 0
	s_setprio 1
	v_mfma_f32_16x16x32_bf16 v[120:123], v[188:191], v[208:211], v[120:123]
	v_mfma_f32_16x16x32_bf16 v[120:123], v[196:199], v[212:215], v[120:123]
	v_mfma_f32_16x16x32_bf16 v[112:115], v[204:207], v[212:215], v[112:115]
	v_mfma_f32_16x16x32_bf16 v[112:115], v[200:203], v[208:211], v[112:115]
	v_mfma_f32_16x16x32_bf16 v[96:99], v[200:203], v[216:219], v[96:99]
	v_mfma_f32_16x16x32_bf16 v[96:99], v[204:207], v[220:223], v[96:99]
	v_mfma_f32_16x16x32_bf16 v[104:107], v[196:199], v[220:223], v[104:107]
	v_mfma_f32_16x16x32_bf16 v[104:107], v[188:191], v[216:219], v[104:107]
	v_mfma_f32_16x16x32_bf16 v[88:91], v[188:191], v[224:227], v[88:91]
	v_mfma_f32_16x16x32_bf16 v[88:91], v[196:199], v[228:231], v[88:91]
	v_mfma_f32_16x16x32_bf16 v[80:83], v[204:207], v[228:231], v[80:83]
	v_mfma_f32_16x16x32_bf16 v[80:83], v[200:203], v[224:227], v[80:83]
	v_mfma_f32_16x16x32_bf16 v[64:67], v[200:203], v[232:235], v[64:67]
	v_mfma_f32_16x16x32_bf16 v[64:67], v[204:207], v[236:239], v[64:67]
	v_mfma_f32_16x16x32_bf16 v[72:75], v[196:199], v[236:239], v[72:75]
	v_mfma_f32_16x16x32_bf16 v[72:75], v[188:191], v[232:235], v[72:75]
	s_setprio 0
	s_barrier
	s_add_i32 s55, s55, s36
	s_mov_b32 m0, s55
	ds_read_b128 v[208:211], v161 offset:49152
	ds_read_b128 v[212:215], v161 offset:50176
	ds_read_b128 v[216:219], v161 offset:51200
	ds_read_b128 v[220:223], v161 offset:52224
	ds_read_b128 v[224:227], v161 offset:53248
	ds_read_b128 v[228:231], v161 offset:54272
	ds_read_b128 v[232:235], v161 offset:55296
	ds_read_b128 v[236:239], v161 offset:56320
	global_load_lds_dwordx4 v152, s[98:99]
	s_add_i32 m0, s55, 0x2000
	s_add_u32 s56, s68, 0x80080
	s_addc_u32 s57, s69, 0
	s_add_i32 s55, s58, s36
	global_load_lds_dwordx4 v156, s[98:99]
	s_mov_b32 m0, s55
	s_nop 0
	global_load_lds_dwordx4 v152, s[56:57]
	s_add_i32 m0, s55, 0x2000
	s_nop 0
	global_load_lds_dwordx4 v156, s[56:57]
	s_mov_b32 m0, s42
	s_nop 0
	global_load_lds_dwordx4 v150, s[100:101]
	s_mov_b32 m0, s43
	s_nop 0
	global_load_lds_dwordx4 v154, s[100:101]
	s_waitcnt vmcnt(8)
	s_waitcnt lgkmcnt(0)
	s_barrier
	s_setprio 1
	s_waitcnt lgkmcnt(0)
	v_mfma_f32_16x16x32_bf16 v[60:63], v[162:165], v[208:211], v[60:63]
	v_mfma_f32_16x16x32_bf16 v[60:63], v[166:169], v[212:215], v[60:63]
	v_mfma_f32_16x16x32_bf16 v[52:55], v[174:177], v[212:215], v[52:55]
	v_mfma_f32_16x16x32_bf16 v[52:55], v[170:173], v[208:211], v[52:55]
	v_mfma_f32_16x16x32_bf16 v[36:39], v[170:173], v[216:219], v[36:39]
	v_mfma_f32_16x16x32_bf16 v[36:39], v[174:177], v[220:223], v[36:39]
	v_mfma_f32_16x16x32_bf16 v[44:47], v[166:169], v[220:223], v[44:47]
	v_mfma_f32_16x16x32_bf16 v[44:47], v[162:165], v[216:219], v[44:47]
	v_mfma_f32_16x16x32_bf16 v[28:31], v[162:165], v[224:227], v[28:31]
	v_mfma_f32_16x16x32_bf16 v[28:31], v[166:169], v[228:231], v[28:31]
	v_mfma_f32_16x16x32_bf16 v[20:23], v[174:177], v[228:231], v[20:23]
	v_mfma_f32_16x16x32_bf16 v[20:23], v[170:173], v[224:227], v[20:23]
	v_mfma_f32_16x16x32_bf16 v[4:7], v[170:173], v[232:235], v[4:7]
	v_mfma_f32_16x16x32_bf16 v[4:7], v[174:177], v[236:239], v[4:7]
	v_mfma_f32_16x16x32_bf16 v[12:15], v[166:169], v[236:239], v[12:15]
	v_mfma_f32_16x16x32_bf16 v[12:15], v[162:165], v[232:235], v[12:15]
	s_setprio 0
	s_setprio 1
	v_mfma_f32_16x16x32_bf16 v[56:59], v[188:191], v[208:211], v[56:59]
	v_mfma_f32_16x16x32_bf16 v[56:59], v[196:199], v[212:215], v[56:59]
	v_mfma_f32_16x16x32_bf16 v[48:51], v[204:207], v[212:215], v[48:51]
	v_mfma_f32_16x16x32_bf16 v[48:51], v[200:203], v[208:211], v[48:51]
	v_mfma_f32_16x16x32_bf16 v[32:35], v[200:203], v[216:219], v[32:35]
	v_mfma_f32_16x16x32_bf16 v[32:35], v[204:207], v[220:223], v[32:35]
	v_mfma_f32_16x16x32_bf16 v[40:43], v[196:199], v[220:223], v[40:43]
	v_mfma_f32_16x16x32_bf16 v[40:43], v[188:191], v[216:219], v[40:43]
	v_mfma_f32_16x16x32_bf16 v[24:27], v[188:191], v[224:227], v[24:27]
	v_mfma_f32_16x16x32_bf16 v[24:27], v[196:199], v[228:231], v[24:27]
	v_mfma_f32_16x16x32_bf16 v[16:19], v[204:207], v[228:231], v[16:19]
	v_mfma_f32_16x16x32_bf16 v[16:19], v[200:203], v[224:227], v[16:19]
	v_mfma_f32_16x16x32_bf16 v[0:3], v[200:203], v[232:235], v[0:3]
	v_mfma_f32_16x16x32_bf16 v[0:3], v[204:207], v[236:239], v[0:3]
	v_mfma_f32_16x16x32_bf16 v[8:11], v[196:199], v[236:239], v[8:11]
	v_mfma_f32_16x16x32_bf16 v[8:11], v[188:191], v[232:235], v[8:11]
	s_setprio 0
	s_barrier
	s_add_i32 s54, s54, 2
	s_add_u32 s66, s66, 0x100
	s_addc_u32 s67, s67, 0
	s_add_u32 s52, s52, 0x100
	s_addc_u32 s53, s53, 0
	s_cmp_gt_u32 s54, 29
	s_cbranch_scc0 .LBB0_192
	s_and_b64 vcc, exec, s[14:15]
	s_cbranch_vccz .LBB0_195
	s_barrier

; #define PG8_STAGE(bufoff, gbase, voff) do { _Pragma("unroll") for (int _i = 0; _i < 2; ++_i) \
;         __builtin_amdgcn_global_load_lds((const unsigned*)((const char*)(gbase) + (voff)[_i]), (PG8_LAS unsigned*)(lds + (bufoff) + ldsw + _i * 8192), 16, 0, 0); } while (0)
; #define PG8_LDA(dst, b, h) do { _Pragma("unroll") for (int m = 0; m < 4; ++m) _Pragma("unroll") for (int k = 0; k < 2; ++k) dst[m][k] = *(const PG8_LAS bf16x8*)(lds + PG8_SA(b, h) + aoff + m * 2048 + k * 1024); } while (0)
; #define PG8_LDB(dst, b, h) do { _Pragma("unroll") for (int n = 0; n < 2; ++n) _Pragma("unroll") for (int k = 0; k < 2; ++k) dst[n][k] = *(const PG8_LAS bf16x8*)(lds + PG8_SB(b, h) + boff + n * 2048 + k * 1024); } while (0)
; #define PG8_MMA(ai, bj, At, Bt) do { __builtin_amdgcn_s_setprio(1); _Pragma("unroll") for (int m = 0; m < 4; ++m) _Pragma("unroll") for (int n = 0; n < 2; ++n) _Pragma("unroll") for (int k = 0; k < 2; ++k) \
;         acc[ai][bj][m][n] = __builtin_amdgcn_mfma_f32_16x16x32_bf16(Bt[n][k], At[m][k], acc[ai][bj][m][n], 0, 0, 0); __builtin_amdgcn_s_setprio(0); } while (0)
; #define PG8_WAIT_V(n) asm volatile("s_waitcnt vmcnt(" #n ")" ::: "memory")
; #define PG8_BAR __builtin_amdgcn_s_barrier()
; template <class Epi, class Sched, bool ALIGN_EPI = false, bool SP2 = false>
; __device__ __forceinline__ void gemm_phase(PG8_LAS unsigned char* lds, const Gemm g, const Sched& S, const Epi& E) {
;     ...
;         for (int t = 0; t < nt; t += 2) {
;             const bool last = (t == nt - 2);
;             const char* a1 = cA + (size_t)(t + 1) * kstep;
;             const char* a2 = last ? nA : cA + (size_t)(t + 2) * kstep; const char* b2 = last ? nB : cB + (size_t)(t + 2) * kstep;
;             const char* a3 = a2 + kstep; const char* b3 = b2 + kstep;
;             if (last && has_next) S.a_ready(nxt);
;             if constexpr (SP2) {
;             PG8_LDB(B0, 0, 0); PG8_LDB(B1, 0, 1); PG8_SCHED; PG8_LDA(At, 0, 0); PG8_STAGE(PG8_SA(1, 1), a1 + hstep, voffA);
;             PG8_WAIT_V(8); PG8_WAIT_L(0); PG8_BAR; PG8_MMA(0, 0, At, B0); PG8_MMA(0, 1, At, B1); PG8_BAR; PG8_SCHED;
;             PG8_LDA(At, 0, 1); PG8_STAGE(PG8_SB(0, 0), b2, voffB); PG8_STAGE(PG8_SB(0, 1), b2 + hstep, voffB); PG8_STAGE(PG8_SA(0, 0), a2, voffA);
;             PG8_WAIT_V(8); PG8_WAIT_L(0); PG8_BAR; PG8_MMA(1, 0, At, B0); PG8_MMA(1, 1, At, B1); PG8_BAR; PG8_SCHED;
.LBB0_308:
	ds_read_b128 v[128:131], v155
	ds_read_b128 v[132:135], v155 offset:1024
	ds_read_b128 v[170:173], v155 offset:2048
	ds_read_b128 v[174:177], v155 offset:3072
	ds_read_b128 v[196:199], v157
	ds_read_b128 v[200:203], v157 offset:1024
	ds_read_b128 v[204:207], v157 offset:2048
	ds_read_b128 v[208:211], v157 offset:3072
	s_add_u32 s12, s10, 0xffea0080
	s_addc_u32 s13, s11, -1
	s_cmpk_eq_i32 s40, 0x54
	s_cselect_b32 s15, s77, s13
	s_cselect_b32 s14, s76, s12
	s_cselect_b32 s13, s79, s39
	s_cselect_b32 s12, s78, s17
	s_add_i32 m0, s54, 0xc000
	ds_read_b128 v[212:215], v161
	ds_read_b128 v[216:219], v161 offset:1024
	ds_read_b128 v[220:223], v161 offset:2048
	ds_read_b128 v[224:227], v161 offset:3072
	ds_read_b128 v[228:231], v161 offset:4096
	ds_read_b128 v[232:235], v161 offset:5120
	ds_read_b128 v[236:239], v161 offset:6144
	ds_read_b128 v[240:243], v161 offset:7168
	global_load_lds_dwordx4 v162, s[10:11]
	s_add_i32 m0, s54, 0xe000
	s_nop 0
	global_load_lds_dwordx4 v164, s[10:11]
	s_waitcnt vmcnt(8)
	s_waitcnt lgkmcnt(0)
	s_barrier
	s_setprio 1
	s_waitcnt lgkmcnt(0)
	v_mfma_f32_16x16x32_bf16 v[124:127], v[128:131], v[212:215], v[124:127]
	v_mfma_f32_16x16x32_bf16 v[124:127], v[132:135], v[216:219], v[124:127]
	v_mfma_f32_16x16x32_bf16 v[120:123], v[174:177], v[216:219], v[120:123]
	v_mfma_f32_16x16x32_bf16 v[120:123], v[170:173], v[212:215], v[120:123]
	v_mfma_f32_16x16x32_bf16 v[104:107], v[170:173], v[220:223], v[104:107]
	v_mfma_f32_16x16x32_bf16 v[104:107], v[174:177], v[224:227], v[104:107]
	v_mfma_f32_16x16x32_bf16 v[108:111], v[132:135], v[224:227], v[108:111]
	v_mfma_f32_16x16x32_bf16 v[108:111], v[128:131], v[220:223], v[108:111]
	v_mfma_f32_16x16x32_bf16 v[92:95], v[128:131], v[228:231], v[92:95]
	v_mfma_f32_16x16x32_bf16 v[92:95], v[132:135], v[232:235], v[92:95]
	v_mfma_f32_16x16x32_bf16 v[88:91], v[174:177], v[232:235], v[88:91]
	v_mfma_f32_16x16x32_bf16 v[88:91], v[170:173], v[228:231], v[88:91]
	v_mfma_f32_16x16x32_bf16 v[72:75], v[170:173], v[236:239], v[72:75]
	v_mfma_f32_16x16x32_bf16 v[72:75], v[174:177], v[240:243], v[72:75]
	v_mfma_f32_16x16x32_bf16 v[76:79], v[132:135], v[240:243], v[76:79]
	v_mfma_f32_16x16x32_bf16 v[76:79], v[128:131], v[236:239], v[76:79]
	s_setprio 0
	s_setprio 1
	v_mfma_f32_16x16x32_bf16 v[116:119], v[196:199], v[212:215], v[116:119]
	v_mfma_f32_16x16x32_bf16 v[116:119], v[200:203], v[216:219], v[116:119]
	v_mfma_f32_16x16x32_bf16 v[112:115], v[208:211], v[216:219], v[112:115]
	v_mfma_f32_16x16x32_bf16 v[112:115], v[204:207], v[212:215], v[112:115]
	v_mfma_f32_16x16x32_bf16 v[96:99], v[204:207], v[220:223], v[96:99]
	v_mfma_f32_16x16x32_bf16 v[96:99], v[208:211], v[224:227], v[96:99]
	v_mfma_f32_16x16x32_bf16 v[100:103], v[200:203], v[224:227], v[100:103]
	v_mfma_f32_16x16x32_bf16 v[100:103], v[196:199], v[220:223], v[100:103]
	v_mfma_f32_16x16x32_bf16 v[84:87], v[196:199], v[228:231], v[84:87]
	v_mfma_f32_16x16x32_bf16 v[84:87], v[200:203], v[232:235], v[84:87]
	v_mfma_f32_16x16x32_bf16 v[80:83], v[208:211], v[232:235], v[80:83]
	v_mfma_f32_16x16x32_bf16 v[80:83], v[204:207], v[228:231], v[80:83]
	v_mfma_f32_16x16x32_bf16 v[64:67], v[204:207], v[236:239], v[64:67]
	v_mfma_f32_16x16x32_bf16 v[64:67], v[208:211], v[240:243], v[64:67]
	v_mfma_f32_16x16x32_bf16 v[68:71], v[200:203], v[240:243], v[68:71]
	v_mfma_f32_16x16x32_bf16 v[68:71], v[196:199], v[236:239], v[68:71]
	s_setprio 0
	s_barrier
	s_add_u32 s98, s12, 0x80
	s_addc_u32 s99, s13, 0
	s_add_u32 s100, s14, 0x80
	s_addc_u32 s101, s15, 0
	s_add_i32 s41, s92, s53
	s_mov_b32 m0, s41
	ds_read_b128 v[212:215], v161 offset:16384
	ds_read_b128 v[216:219], v161 offset:17408
	ds_read_b128 v[220:223], v161 offset:18432
	ds_read_b128 v[224:227], v161 offset:19456
	ds_read_b128 v[228:231], v161 offset:20480
	ds_read_b128 v[232:235], v161 offset:21504
	ds_read_b128 v[236:239], v161 offset:22528
	ds_read_b128 v[240:243], v161 offset:23552
	global_load_lds_dwordx4 v144, s[12:13]
	s_add_i32 m0, s41, 0x2000
	s_add_u32 s42, s12, 0x160000
	s_addc_u32 s43, s13, 0
	s_add_i32 s41, s93, s53
	global_load_lds_dwordx4 v148, s[12:13]
	s_mov_b32 m0, s41
	s_nop 0
	global_load_lds_dwordx4 v144, s[42:43]
	s_add_i32 m0, s41, 0x2000
	s_nop 0
	global_load_lds_dwordx4 v148, s[42:43]
	s_mov_b32 m0, s54
	s_nop 0
	global_load_lds_dwordx4 v142, s[14:15]
	s_mov_b32 m0, s55
	s_nop 0
	global_load_lds_dwordx4 v146, s[14:15]
	s_waitcnt vmcnt(8)
	s_waitcnt lgkmcnt(0)
	s_barrier
	s_setprio 1
	s_waitcnt lgkmcnt(0)
	v_mfma_f32_16x16x32_bf16 v[60:63], v[128:131], v[212:215], v[60:63]
	v_mfma_f32_16x16x32_bf16 v[60:63], v[132:135], v[216:219], v[60:63]
	v_mfma_f32_16x16x32_bf16 v[56:59], v[174:177], v[216:219], v[56:59]
	v_mfma_f32_16x16x32_bf16 v[56:59], v[170:173], v[212:215], v[56:59]
	v_mfma_f32_16x16x32_bf16 v[40:43], v[170:173], v[220:223], v[40:43]
	v_mfma_f32_16x16x32_bf16 v[40:43], v[174:177], v[224:227], v[40:43]
	v_mfma_f32_16x16x32_bf16 v[44:47], v[132:135], v[224:227], v[44:47]
	v_mfma_f32_16x16x32_bf16 v[44:47], v[128:131], v[220:223], v[44:47]
	v_mfma_f32_16x16x32_bf16 v[28:31], v[128:131], v[228:231], v[28:31]
	v_mfma_f32_16x16x32_bf16 v[28:31], v[132:135], v[232:235], v[28:31]
	v_mfma_f32_16x16x32_bf16 v[24:27], v[174:177], v[232:235], v[24:27]
	v_mfma_f32_16x16x32_bf16 v[24:27], v[170:173], v[228:231], v[24:27]
	v_mfma_f32_16x16x32_bf16 v[8:11], v[170:173], v[236:239], v[8:11]
	v_mfma_f32_16x16x32_bf16 v[8:11], v[174:177], v[240:243], v[8:11]
	v_mfma_f32_16x16x32_bf16 v[12:15], v[132:135], v[240:243], v[12:15]
	v_mfma_f32_16x16x32_bf16 v[12:15], v[128:131], v[236:239], v[12:15]
	s_setprio 0
	s_setprio 1
	v_mfma_f32_16x16x32_bf16 v[52:55], v[196:199], v[212:215], v[52:55]
	v_mfma_f32_16x16x32_bf16 v[52:55], v[200:203], v[216:219], v[52:55]
	v_mfma_f32_16x16x32_bf16 v[48:51], v[208:211], v[216:219], v[48:51]
	v_mfma_f32_16x16x32_bf16 v[48:51], v[204:207], v[212:215], v[48:51]
	v_mfma_f32_16x16x32_bf16 v[32:35], v[204:207], v[220:223], v[32:35]
	v_mfma_f32_16x16x32_bf16 v[32:35], v[208:211], v[224:227], v[32:35]
	v_mfma_f32_16x16x32_bf16 v[36:39], v[200:203], v[224:227], v[36:39]
	v_mfma_f32_16x16x32_bf16 v[36:39], v[196:199], v[220:223], v[36:39]
	v_mfma_f32_16x16x32_bf16 v[20:23], v[196:199], v[228:231], v[20:23]
	v_mfma_f32_16x16x32_bf16 v[20:23], v[200:203], v[232:235], v[20:23]
	v_mfma_f32_16x16x32_bf16 v[16:19], v[208:211], v[232:235], v[16:19]
	v_mfma_f32_16x16x32_bf16 v[16:19], v[204:207], v[228:231], v[16:19]
	v_mfma_f32_16x16x32_bf16 v[0:3], v[204:207], v[236:239], v[0:3]
	v_mfma_f32_16x16x32_bf16 v[0:3], v[208:211], v[240:243], v[0:3]
	v_mfma_f32_16x16x32_bf16 v[4:7], v[200:203], v[240:243], v[4:7]
	v_mfma_f32_16x16x32_bf16 v[4:7], v[196:199], v[236:239], v[4:7]
	s_setprio 0
	s_barrier
; #define PG8_STAGE(bufoff, gbase, voff) do { _Pragma("unroll") for (int _i = 0; _i < 2; ++_i) \
;         __builtin_amdgcn_global_load_lds((const unsigned*)((const char*)(gbase) + (voff)[_i]), (PG8_LAS unsigned*)(lds + (bufoff) + ldsw + _i * 8192), 16, 0, 0); } while (0)
; #define PG8_LDA(dst, b, h) do { _Pragma("unroll") for (int m = 0; m < 4; ++m) _Pragma("unroll") for (int k = 0; k < 2; ++k) dst[m][k] = *(const PG8_LAS bf16x8*)(lds + PG8_SA(b, h) + aoff + m * 2048 + k * 1024); } while (0)
; #define PG8_LDB(dst, b, h) do { _Pragma("unroll") for (int n = 0; n < 2; ++n) _Pragma("unroll") for (int k = 0; k < 2; ++k) dst[n][k] = *(const PG8_LAS bf16x8*)(lds + PG8_SB(b, h) + boff + n * 2048 + k * 1024); } while (0)
; #define PG8_MMA(ai, bj, At, Bt) do { __builtin_amdgcn_s_setprio(1); _Pragma("unroll") for (int m = 0; m < 4; ++m) _Pragma("unroll") for (int n = 0; n < 2; ++n) _Pragma("unroll") for (int k = 0; k < 2; ++k) \
;         acc[ai][bj][m][n] = __builtin_amdgcn_mfma_f32_16x16x32_bf16(Bt[n][k], At[m][k], acc[ai][bj][m][n], 0, 0, 0); __builtin_amdgcn_s_setprio(0); } while (0)
; #define PG8_WAIT_V(n) asm volatile("s_waitcnt vmcnt(" #n ")" ::: "memory")
; #define PG8_WAIT_L(n) asm volatile("s_waitcnt lgkmcnt(" #n ")" ::: "memory")
; #define PG8_BAR __builtin_amdgcn_s_barrier()
; #define PG8_SCHED __builtin_amdgcn_sched_barrier(0)
; template <class Epi, class Sched, bool ALIGN_EPI = false, bool SP2 = false>
; __device__ __forceinline__ void gemm_phase(PG8_LAS unsigned char* lds, const Gemm g, const Sched& S, const Epi& E) {
;     ...
;             PG8_LDB(B0, 1, 0); PG8_LDB(B1, 1, 1); PG8_SCHED; PG8_LDA(At, 1, 0); PG8_STAGE(PG8_SA(0, 1), a2 + hstep, voffA);
;             PG8_WAIT_V(8); PG8_WAIT_L(0); PG8_BAR; PG8_MMA(0, 0, At, B0); PG8_MMA(0, 1, At, B1); PG8_BAR; PG8_SCHED;
;             PG8_LDA(At, 1, 1); PG8_STAGE(PG8_SB(1, 0), b3, voffB); PG8_STAGE(PG8_SB(1, 1), b3 + hstep, voffB); PG8_STAGE(PG8_SA(1, 0), a3, voffA);
;             PG8_WAIT_V(8); PG8_WAIT_L(0); PG8_BAR; PG8_MMA(1, 0, At, B0); PG8_MMA(1, 1, At, B1); PG8_BAR; PG8_SCHED;
;     ...
;         if constexpr (ALIGN_EPI) { if (wr == 0) PG8_BAR; }
	s_add_i32 s41, 0, 0x18000
	v_add_u32_e32 v158, s41, v151
	s_add_i32 s42, 0, 0x1c000
	ds_read_b128 v[128:131], v158
	ds_read_b128 v[132:135], v158 offset:1024
	ds_read_b128 v[170:173], v158 offset:2048
	ds_read_b128 v[174:177], v158 offset:3072
	v_add_u32_e32 v158, s42, v151
	ds_read_b128 v[196:199], v158
	ds_read_b128 v[200:203], v158 offset:1024
	ds_read_b128 v[204:207], v158 offset:2048
	ds_read_b128 v[208:211], v158 offset:3072
	s_add_u32 s14, s14, 0x160000
	s_addc_u32 s15, s15, 0
	s_mov_b32 m0, s56
	ds_read_b128 v[212:215], v161 offset:32768
	ds_read_b128 v[216:219], v161 offset:33792
	ds_read_b128 v[220:223], v161 offset:34816
	ds_read_b128 v[224:227], v161 offset:35840
	ds_read_b128 v[228:231], v161 offset:36864
	ds_read_b128 v[232:235], v161 offset:37888
	ds_read_b128 v[236:239], v161 offset:38912
	ds_read_b128 v[240:243], v161 offset:39936
	global_load_lds_dwordx4 v142, s[14:15]
	s_mov_b32 m0, s57
	s_nop 0
	global_load_lds_dwordx4 v146, s[14:15]
	s_waitcnt vmcnt(8)
	s_waitcnt lgkmcnt(0)
	s_barrier
	s_setprio 1
	s_waitcnt lgkmcnt(0)
	v_mfma_f32_16x16x32_bf16 v[124:127], v[128:131], v[212:215], v[124:127]
	v_mfma_f32_16x16x32_bf16 v[124:127], v[132:135], v[216:219], v[124:127]
	v_mfma_f32_16x16x32_bf16 v[120:123], v[174:177], v[216:219], v[120:123]
	v_mfma_f32_16x16x32_bf16 v[120:123], v[170:173], v[212:215], v[120:123]
	v_mfma_f32_16x16x32_bf16 v[104:107], v[170:173], v[220:223], v[104:107]
	v_mfma_f32_16x16x32_bf16 v[104:107], v[174:177], v[224:227], v[104:107]
	v_mfma_f32_16x16x32_bf16 v[108:111], v[132:135], v[224:227], v[108:111]
	v_mfma_f32_16x16x32_bf16 v[108:111], v[128:131], v[220:223], v[108:111]
	v_mfma_f32_16x16x32_bf16 v[92:95], v[128:131], v[228:231], v[92:95]
	v_mfma_f32_16x16x32_bf16 v[92:95], v[132:135], v[232:235], v[92:95]
	v_mfma_f32_16x16x32_bf16 v[88:91], v[174:177], v[232:235], v[88:91]
	v_mfma_f32_16x16x32_bf16 v[88:91], v[170:173], v[228:231], v[88:91]
	v_mfma_f32_16x16x32_bf16 v[72:75], v[170:173], v[236:239], v[72:75]
	v_mfma_f32_16x16x32_bf16 v[72:75], v[174:177], v[240:243], v[72:75]
	v_mfma_f32_16x16x32_bf16 v[76:79], v[132:135], v[240:243], v[76:79]
	v_mfma_f32_16x16x32_bf16 v[76:79], v[128:131], v[236:239], v[76:79]
	s_setprio 0
	s_setprio 1
	v_mfma_f32_16x16x32_bf16 v[116:119], v[196:199], v[212:215], v[116:119]
	v_mfma_f32_16x16x32_bf16 v[116:119], v[200:203], v[216:219], v[116:119]
	v_mfma_f32_16x16x32_bf16 v[112:115], v[208:211], v[216:219], v[112:115]
	v_mfma_f32_16x16x32_bf16 v[112:115], v[204:207], v[212:215], v[112:115]
	v_mfma_f32_16x16x32_bf16 v[96:99], v[204:207], v[220:223], v[96:99]
	v_mfma_f32_16x16x32_bf16 v[96:99], v[208:211], v[224:227], v[96:99]
	v_mfma_f32_16x16x32_bf16 v[100:103], v[200:203], v[224:227], v[100:103]
	v_mfma_f32_16x16x32_bf16 v[100:103], v[196:199], v[220:223], v[100:103]
	v_mfma_f32_16x16x32_bf16 v[84:87], v[196:199], v[228:231], v[84:87]
	v_mfma_f32_16x16x32_bf16 v[84:87], v[200:203], v[232:235], v[84:87]
	v_mfma_f32_16x16x32_bf16 v[80:83], v[208:211], v[232:235], v[80:83]
	v_mfma_f32_16x16x32_bf16 v[80:83], v[204:207], v[228:231], v[80:83]
	v_mfma_f32_16x16x32_bf16 v[64:67], v[204:207], v[236:239], v[64:67]
	v_mfma_f32_16x16x32_bf16 v[64:67], v[208:211], v[240:243], v[64:67]
	v_mfma_f32_16x16x32_bf16 v[68:71], v[200:203], v[240:243], v[68:71]
	v_mfma_f32_16x16x32_bf16 v[68:71], v[196:199], v[236:239], v[68:71]
	s_setprio 0
	s_barrier
	s_add_i32 s14, s41, s53
	s_mov_b32 m0, s14
	ds_read_b128 v[212:215], v161 offset:49152
	ds_read_b128 v[216:219], v161 offset:50176
	ds_read_b128 v[220:223], v161 offset:51200
	ds_read_b128 v[224:227], v161 offset:52224
	ds_read_b128 v[228:231], v161 offset:53248
	ds_read_b128 v[232:235], v161 offset:54272
	ds_read_b128 v[236:239], v161 offset:55296
	ds_read_b128 v[240:243], v161 offset:56320
	global_load_lds_dwordx4 v144, s[98:99]
	s_add_i32 m0, s14, 0x2000
	s_add_u32 s12, s12, 0x160080
	s_addc_u32 s13, s13, 0
	s_add_i32 s14, s42, s53
	global_load_lds_dwordx4 v148, s[98:99]
	s_mov_b32 m0, s14
	s_nop 0
	global_load_lds_dwordx4 v144, s[12:13]
	s_add_i32 m0, s14, 0x2000
	s_nop 0
	global_load_lds_dwordx4 v148, s[12:13]
	s_mov_b32 m0, s84
	s_nop 0
	global_load_lds_dwordx4 v142, s[100:101]
	s_mov_b32 m0, s85
	s_nop 0
	global_load_lds_dwordx4 v146, s[100:101]
	s_waitcnt vmcnt(8)
	s_waitcnt lgkmcnt(0)
	s_barrier
	s_setprio 1
	s_waitcnt lgkmcnt(0)
	v_mfma_f32_16x16x32_bf16 v[60:63], v[128:131], v[212:215], v[60:63]
	v_mfma_f32_16x16x32_bf16 v[60:63], v[132:135], v[216:219], v[60:63]
	v_mfma_f32_16x16x32_bf16 v[56:59], v[174:177], v[216:219], v[56:59]
	v_mfma_f32_16x16x32_bf16 v[56:59], v[170:173], v[212:215], v[56:59]
	v_mfma_f32_16x16x32_bf16 v[40:43], v[170:173], v[220:223], v[40:43]
	v_mfma_f32_16x16x32_bf16 v[40:43], v[174:177], v[224:227], v[40:43]
	v_mfma_f32_16x16x32_bf16 v[44:47], v[132:135], v[224:227], v[44:47]
	v_mfma_f32_16x16x32_bf16 v[44:47], v[128:131], v[220:223], v[44:47]
	v_mfma_f32_16x16x32_bf16 v[28:31], v[128:131], v[228:231], v[28:31]
	v_mfma_f32_16x16x32_bf16 v[28:31], v[132:135], v[232:235], v[28:31]
	v_mfma_f32_16x16x32_bf16 v[24:27], v[174:177], v[232:235], v[24:27]
	v_mfma_f32_16x16x32_bf16 v[24:27], v[170:173], v[228:231], v[24:27]
	v_mfma_f32_16x16x32_bf16 v[8:11], v[170:173], v[236:239], v[8:11]
	v_mfma_f32_16x16x32_bf16 v[8:11], v[174:177], v[240:243], v[8:11]
	v_mfma_f32_16x16x32_bf16 v[12:15], v[132:135], v[240:243], v[12:15]
	v_mfma_f32_16x16x32_bf16 v[12:15], v[128:131], v[236:239], v[12:15]
	s_setprio 0
	s_setprio 1
	v_mfma_f32_16x16x32_bf16 v[52:55], v[196:199], v[212:215], v[52:55]
	v_mfma_f32_16x16x32_bf16 v[52:55], v[200:203], v[216:219], v[52:55]
	v_mfma_f32_16x16x32_bf16 v[48:51], v[208:211], v[216:219], v[48:51]
	v_mfma_f32_16x16x32_bf16 v[48:51], v[204:207], v[212:215], v[48:51]
	v_mfma_f32_16x16x32_bf16 v[32:35], v[204:207], v[220:223], v[32:35]
	v_mfma_f32_16x16x32_bf16 v[32:35], v[208:211], v[224:227], v[32:35]
	v_mfma_f32_16x16x32_bf16 v[36:39], v[200:203], v[224:227], v[36:39]
	v_mfma_f32_16x16x32_bf16 v[36:39], v[196:199], v[220:223], v[36:39]
	v_mfma_f32_16x16x32_bf16 v[20:23], v[196:199], v[228:231], v[20:23]
	v_mfma_f32_16x16x32_bf16 v[20:23], v[200:203], v[232:235], v[20:23]
	v_mfma_f32_16x16x32_bf16 v[16:19], v[208:211], v[232:235], v[16:19]
	v_mfma_f32_16x16x32_bf16 v[16:19], v[204:207], v[228:231], v[16:19]
	v_mfma_f32_16x16x32_bf16 v[0:3], v[204:207], v[236:239], v[0:3]
	v_mfma_f32_16x16x32_bf16 v[0:3], v[208:211], v[240:243], v[0:3]
	v_mfma_f32_16x16x32_bf16 v[4:7], v[200:203], v[240:243], v[4:7]
	v_mfma_f32_16x16x32_bf16 v[4:7], v[196:199], v[236:239], v[4:7]
	s_setprio 0
	s_barrier
	s_add_i32 s40, s40, 2
	s_add_u32 s10, s10, 0x100
	s_addc_u32 s11, s11, 0
	s_add_u32 s17, s17, 0x100
	s_addc_u32 s39, s39, 0
	s_cmpk_gt_u32 s40, 0x55
	s_cbranch_scc0 .LBB0_308
	s_and_b64 vcc, exec, s[74:75]
	s_cbranch_vccz .LBB0_311
	s_barrier

; #define PG8_STAGE(bufoff, gbase, voff) do { _Pragma("unroll") for (int _i = 0; _i < 2; ++_i) \
;         __builtin_amdgcn_global_load_lds((const unsigned*)((const char*)(gbase) + (voff)[_i]), (PG8_LAS unsigned*)(lds + (bufoff) + ldsw + _i * 8192), 16, 0, 0); } while (0)
; #define PG8_LDA(dst, b, h) do { _Pragma("unroll") for (int m = 0; m < 4; ++m) _Pragma("unroll") for (int k = 0; k < 2; ++k) dst[m][k] = *(const PG8_LAS bf16x8*)(lds + PG8_SA(b, h) + aoff + m * 2048 + k * 1024); } while (0)
; #define PG8_LDB(dst, b, h) do { _Pragma("unroll") for (int n = 0; n < 2; ++n) _Pragma("unroll") for (int k = 0; k < 2; ++k) dst[n][k] = *(const PG8_LAS bf16x8*)(lds + PG8_SB(b, h) + boff + n * 2048 + k * 1024); } while (0)
; #define PG8_MMA(ai, bj, At, Bt) do { __builtin_amdgcn_s_setprio(1); _Pragma("unroll") for (int m = 0; m < 4; ++m) _Pragma("unroll") for (int n = 0; n < 2; ++n) _Pragma("unroll") for (int k = 0; k < 2; ++k) \
;         acc[ai][bj][m][n] = __builtin_amdgcn_mfma_f32_16x16x32_bf16(Bt[n][k], At[m][k], acc[ai][bj][m][n], 0, 0, 0); __builtin_amdgcn_s_setprio(0); } while (0)
; #define PG8_WAIT_V(n) asm volatile("s_waitcnt vmcnt(" #n ")" ::: "memory")
; #define PG8_BAR __builtin_amdgcn_s_barrier()
; template <class Epi, class Sched, bool ALIGN_EPI = false, bool SP2 = false>
; __device__ __forceinline__ void gemm_phase(PG8_LAS unsigned char* lds, const Gemm g, const Sched& S, const Epi& E) {
;     ...
;         for (int t = 0; t < nt; t += 2) {
;             const bool last = (t == nt - 2);
;             const char* a1 = cA + (size_t)(t + 1) * kstep;
;             const char* a2 = last ? nA : cA + (size_t)(t + 2) * kstep; const char* b2 = last ? nB : cB + (size_t)(t + 2) * kstep;
;             const char* a3 = a2 + kstep; const char* b3 = b2 + kstep;
;             if (last && has_next) S.a_ready(nxt);
;             if constexpr (SP2) {
;             PG8_LDB(B0, 0, 0); PG8_LDB(B1, 0, 1); PG8_SCHED; PG8_LDA(At, 0, 0); PG8_STAGE(PG8_SA(1, 1), a1 + hstep, voffA);
;             PG8_WAIT_V(8); PG8_WAIT_L(0); PG8_BAR; PG8_MMA(0, 0, At, B0); PG8_MMA(0, 1, At, B1); PG8_BAR; PG8_SCHED;
;             PG8_LDA(At, 0, 1); PG8_STAGE(PG8_SB(0, 0), b2, voffB); PG8_STAGE(PG8_SB(0, 1), b2 + hstep, voffB); PG8_STAGE(PG8_SA(0, 0), a2, voffA);
;             PG8_WAIT_V(8); PG8_WAIT_L(0); PG8_BAR; PG8_MMA(1, 0, At, B0); PG8_MMA(1, 1, At, B1); PG8_BAR; PG8_SCHED;
.LBB0_623:
	ds_read_b128 v[162:165], v147
	ds_read_b128 v[166:169], v147 offset:1024
	ds_read_b128 v[172:175], v147 offset:2048
	ds_read_b128 v[196:199], v147 offset:3072
	ds_read_b128 v[200:203], v149
	ds_read_b128 v[204:207], v149 offset:1024
	ds_read_b128 v[208:211], v149 offset:2048
	ds_read_b128 v[212:215], v149 offset:3072
	s_add_u32 s43, s10, 0xfff80080
	s_addc_u32 s44, s11, -1
	s_cmp_eq_u32 s42, 28
	s_cselect_b32 s79, s36, s44
	s_cselect_b32 s78, s37, s43
	s_cselect_b32 s77, s38, s41
	s_cselect_b32 s76, s39, s40
	s_add_i32 m0, s86, 0xc000
	ds_read_b128 v[216:219], v159
	ds_read_b128 v[220:223], v159 offset:1024
	ds_read_b128 v[224:227], v159 offset:2048
	ds_read_b128 v[228:231], v159 offset:3072
	ds_read_b128 v[232:235], v159 offset:4096
	ds_read_b128 v[236:239], v159 offset:5120
	ds_read_b128 v[240:243], v159 offset:6144
	ds_read_b128 v[244:247], v159 offset:7168
	global_load_lds_dwordx4 v132, s[10:11]
	s_add_i32 m0, s86, 0xe000
	s_nop 0
	global_load_lds_dwordx4 v134, s[10:11]
	s_waitcnt vmcnt(8)
	s_waitcnt lgkmcnt(0)
	s_barrier
	s_setprio 1
	s_waitcnt lgkmcnt(0)
	v_mfma_f32_16x16x32_bf16 v[124:127], v[162:165], v[216:219], v[124:127]
	v_mfma_f32_16x16x32_bf16 v[124:127], v[166:169], v[220:223], v[124:127]
	v_mfma_f32_16x16x32_bf16 v[120:123], v[196:199], v[220:223], v[120:123]
	v_mfma_f32_16x16x32_bf16 v[120:123], v[172:175], v[216:219], v[120:123]
	v_mfma_f32_16x16x32_bf16 v[104:107], v[172:175], v[224:227], v[104:107]
	v_mfma_f32_16x16x32_bf16 v[104:107], v[196:199], v[228:231], v[104:107]
	v_mfma_f32_16x16x32_bf16 v[108:111], v[166:169], v[228:231], v[108:111]
	v_mfma_f32_16x16x32_bf16 v[108:111], v[162:165], v[224:227], v[108:111]
	v_mfma_f32_16x16x32_bf16 v[92:95], v[162:165], v[232:235], v[92:95]
	v_mfma_f32_16x16x32_bf16 v[92:95], v[166:169], v[236:239], v[92:95]
	v_mfma_f32_16x16x32_bf16 v[88:91], v[196:199], v[236:239], v[88:91]
	v_mfma_f32_16x16x32_bf16 v[88:91], v[172:175], v[232:235], v[88:91]
	v_mfma_f32_16x16x32_bf16 v[72:75], v[172:175], v[240:243], v[72:75]
	v_mfma_f32_16x16x32_bf16 v[72:75], v[196:199], v[244:247], v[72:75]
	v_mfma_f32_16x16x32_bf16 v[76:79], v[166:169], v[244:247], v[76:79]
	v_mfma_f32_16x16x32_bf16 v[76:79], v[162:165], v[240:243], v[76:79]
	s_setprio 0
	s_setprio 1
	v_mfma_f32_16x16x32_bf16 v[116:119], v[200:203], v[216:219], v[116:119]
	v_mfma_f32_16x16x32_bf16 v[116:119], v[204:207], v[220:223], v[116:119]
	v_mfma_f32_16x16x32_bf16 v[112:115], v[212:215], v[220:223], v[112:115]
	v_mfma_f32_16x16x32_bf16 v[112:115], v[208:211], v[216:219], v[112:115]
	v_mfma_f32_16x16x32_bf16 v[96:99], v[208:211], v[224:227], v[96:99]
	v_mfma_f32_16x16x32_bf16 v[96:99], v[212:215], v[228:231], v[96:99]
	v_mfma_f32_16x16x32_bf16 v[100:103], v[204:207], v[228:231], v[100:103]
	v_mfma_f32_16x16x32_bf16 v[100:103], v[200:203], v[224:227], v[100:103]
	v_mfma_f32_16x16x32_bf16 v[84:87], v[200:203], v[232:235], v[84:87]
	v_mfma_f32_16x16x32_bf16 v[84:87], v[204:207], v[236:239], v[84:87]
	v_mfma_f32_16x16x32_bf16 v[80:83], v[212:215], v[236:239], v[80:83]
	v_mfma_f32_16x16x32_bf16 v[80:83], v[208:211], v[232:235], v[80:83]
	v_mfma_f32_16x16x32_bf16 v[64:67], v[208:211], v[240:243], v[64:67]
	v_mfma_f32_16x16x32_bf16 v[64:67], v[212:215], v[244:247], v[64:67]
	v_mfma_f32_16x16x32_bf16 v[68:71], v[204:207], v[244:247], v[68:71]
	v_mfma_f32_16x16x32_bf16 v[68:71], v[200:203], v[240:243], v[68:71]
	s_setprio 0
	s_barrier
	s_add_u32 s98, s76, 0x80
	s_addc_u32 s99, s77, 0
	s_add_u32 s100, s78, 0x80
	s_addc_u32 s101, s79, 0
	s_add_i32 s43, s3, s85
	s_mov_b32 m0, s43
	ds_read_b128 v[216:219], v159 offset:16384
	ds_read_b128 v[220:223], v159 offset:17408
	ds_read_b128 v[224:227], v159 offset:18432
	ds_read_b128 v[228:231], v159 offset:19456
	ds_read_b128 v[232:235], v159 offset:20480
	ds_read_b128 v[236:239], v159 offset:21504
	ds_read_b128 v[240:243], v159 offset:22528
	ds_read_b128 v[244:247], v159 offset:23552
	global_load_lds_dwordx4 v152, s[76:77]
	s_add_i32 m0, s43, 0x2000
	s_add_u32 s44, s76, 0x80000
	s_addc_u32 s45, s77, 0
	s_add_i32 s43, s52, s85
	global_load_lds_dwordx4 v156, s[76:77]
	s_mov_b32 m0, s43
	s_nop 0
	global_load_lds_dwordx4 v152, s[44:45]
	s_add_i32 m0, s43, 0x2000
	s_nop 0
	global_load_lds_dwordx4 v156, s[44:45]
	s_mov_b32 m0, s86
	s_nop 0
	global_load_lds_dwordx4 v150, s[78:79]
	s_mov_b32 m0, s87
	s_nop 0
	global_load_lds_dwordx4 v154, s[78:79]
	s_waitcnt vmcnt(8)
	s_waitcnt lgkmcnt(0)
	s_barrier
	s_setprio 1
	s_waitcnt lgkmcnt(0)
	v_mfma_f32_16x16x32_bf16 v[60:63], v[162:165], v[216:219], v[60:63]
	v_mfma_f32_16x16x32_bf16 v[60:63], v[166:169], v[220:223], v[60:63]
	v_mfma_f32_16x16x32_bf16 v[56:59], v[196:199], v[220:223], v[56:59]
	v_mfma_f32_16x16x32_bf16 v[56:59], v[172:175], v[216:219], v[56:59]
	v_mfma_f32_16x16x32_bf16 v[40:43], v[172:175], v[224:227], v[40:43]
	v_mfma_f32_16x16x32_bf16 v[40:43], v[196:199], v[228:231], v[40:43]
	v_mfma_f32_16x16x32_bf16 v[44:47], v[166:169], v[228:231], v[44:47]
	v_mfma_f32_16x16x32_bf16 v[44:47], v[162:165], v[224:227], v[44:47]
	v_mfma_f32_16x16x32_bf16 v[28:31], v[162:165], v[232:235], v[28:31]
	v_mfma_f32_16x16x32_bf16 v[28:31], v[166:169], v[236:239], v[28:31]
	v_mfma_f32_16x16x32_bf16 v[24:27], v[196:199], v[236:239], v[24:27]
	v_mfma_f32_16x16x32_bf16 v[24:27], v[172:175], v[232:235], v[24:27]
	v_mfma_f32_16x16x32_bf16 v[4:7], v[172:175], v[240:243], v[4:7]
	v_mfma_f32_16x16x32_bf16 v[4:7], v[196:199], v[244:247], v[4:7]
	v_mfma_f32_16x16x32_bf16 v[12:15], v[166:169], v[244:247], v[12:15]
	v_mfma_f32_16x16x32_bf16 v[12:15], v[162:165], v[240:243], v[12:15]
	s_setprio 0
	s_setprio 1
	v_mfma_f32_16x16x32_bf16 v[52:55], v[200:203], v[216:219], v[52:55]
	v_mfma_f32_16x16x32_bf16 v[52:55], v[204:207], v[220:223], v[52:55]
	v_mfma_f32_16x16x32_bf16 v[48:51], v[212:215], v[220:223], v[48:51]
	v_mfma_f32_16x16x32_bf16 v[48:51], v[208:211], v[216:219], v[48:51]
	v_mfma_f32_16x16x32_bf16 v[32:35], v[208:211], v[224:227], v[32:35]
	v_mfma_f32_16x16x32_bf16 v[32:35], v[212:215], v[228:231], v[32:35]
	v_mfma_f32_16x16x32_bf16 v[36:39], v[204:207], v[228:231], v[36:39]
	v_mfma_f32_16x16x32_bf16 v[36:39], v[200:203], v[224:227], v[36:39]
	v_mfma_f32_16x16x32_bf16 v[20:23], v[200:203], v[232:235], v[20:23]
	v_mfma_f32_16x16x32_bf16 v[20:23], v[204:207], v[236:239], v[20:23]
	v_mfma_f32_16x16x32_bf16 v[16:19], v[212:215], v[236:239], v[16:19]
	v_mfma_f32_16x16x32_bf16 v[16:19], v[208:211], v[232:235], v[16:19]
	v_mfma_f32_16x16x32_bf16 v[0:3], v[208:211], v[240:243], v[0:3]
	v_mfma_f32_16x16x32_bf16 v[0:3], v[212:215], v[244:247], v[0:3]
	v_mfma_f32_16x16x32_bf16 v[8:11], v[204:207], v[244:247], v[8:11]
	v_mfma_f32_16x16x32_bf16 v[8:11], v[200:203], v[240:243], v[8:11]
	s_setprio 0
	s_barrier
; #define PG8_STAGE(bufoff, gbase, voff) do { _Pragma("unroll") for (int _i = 0; _i < 2; ++_i) \
;         __builtin_amdgcn_global_load_lds((const unsigned*)((const char*)(gbase) + (voff)[_i]), (PG8_LAS unsigned*)(lds + (bufoff) + ldsw + _i * 8192), 16, 0, 0); } while (0)
; #define PG8_LDA(dst, b, h) do { _Pragma("unroll") for (int m = 0; m < 4; ++m) _Pragma("unroll") for (int k = 0; k < 2; ++k) dst[m][k] = *(const PG8_LAS bf16x8*)(lds + PG8_SA(b, h) + aoff + m * 2048 + k * 1024); } while (0)
; #define PG8_LDB(dst, b, h) do { _Pragma("unroll") for (int n = 0; n < 2; ++n) _Pragma("unroll") for (int k = 0; k < 2; ++k) dst[n][k] = *(const PG8_LAS bf16x8*)(lds + PG8_SB(b, h) + boff + n * 2048 + k * 1024); } while (0)
; #define PG8_MMA(ai, bj, At, Bt) do { __builtin_amdgcn_s_setprio(1); _Pragma("unroll") for (int m = 0; m < 4; ++m) _Pragma("unroll") for (int n = 0; n < 2; ++n) _Pragma("unroll") for (int k = 0; k < 2; ++k) \
;         acc[ai][bj][m][n] = __builtin_amdgcn_mfma_f32_16x16x32_bf16(Bt[n][k], At[m][k], acc[ai][bj][m][n], 0, 0, 0); __builtin_amdgcn_s_setprio(0); } while (0)
; #define PG8_WAIT_V(n) asm volatile("s_waitcnt vmcnt(" #n ")" ::: "memory")
; #define PG8_WAIT_L(n) asm volatile("s_waitcnt lgkmcnt(" #n ")" ::: "memory")
; #define PG8_BAR __builtin_amdgcn_s_barrier()
; #define PG8_SCHED __builtin_amdgcn_sched_barrier(0)
;     __device__ __forceinline__ void operator()(const f32x4 (&acc)[2][2][4][2], const Unit& u, int wr, int wc, int fr, int fq) const {
;         const int row0 = u.pm * BM + wr * 64 + fr, pn = u.pn, cw = wc * 32 + 8 * fq;
;         if (pn >= 10) {
; template <class Epi, class Sched, bool ALIGN_EPI = false, bool SP2 = false>
; __device__ __forceinline__ void gemm_phase(PG8_LAS unsigned char* lds, const Gemm g, const Sched& S, const Epi& E) {
;     ...
;             PG8_LDB(B0, 1, 0); PG8_LDB(B1, 1, 1); PG8_SCHED; PG8_LDA(At, 1, 0); PG8_STAGE(PG8_SA(0, 1), a2 + hstep, voffA);
;             PG8_WAIT_V(8); PG8_WAIT_L(0); PG8_BAR; PG8_MMA(0, 0, At, B0); PG8_MMA(0, 1, At, B1); PG8_BAR; PG8_SCHED;
;             PG8_LDA(At, 1, 1); PG8_STAGE(PG8_SB(1, 0), b3, voffB); PG8_STAGE(PG8_SB(1, 1), b3 + hstep, voffB); PG8_STAGE(PG8_SA(1, 0), a3, voffA);
;             PG8_WAIT_V(8); PG8_WAIT_L(0); PG8_BAR; PG8_MMA(1, 0, At, B0); PG8_MMA(1, 1, At, B1); PG8_BAR; PG8_SCHED;
	s_add_i32 s43, 0, 0x18000
	v_add_u32_e32 v128, s43, v145
	s_add_i32 s46, 0, 0x1c000
	ds_read_b128 v[162:165], v128
	ds_read_b128 v[166:169], v128 offset:1024
	ds_read_b128 v[172:175], v128 offset:2048
	ds_read_b128 v[196:199], v128 offset:3072
	v_add_u32_e32 v128, s46, v145
	ds_read_b128 v[200:203], v128
	ds_read_b128 v[204:207], v128 offset:1024
	ds_read_b128 v[208:211], v128 offset:2048
	ds_read_b128 v[212:215], v128 offset:3072
	s_add_u32 s44, s78, 0x80000
	s_addc_u32 s45, s79, 0
	s_mov_b32 m0, s91
	ds_read_b128 v[216:219], v159 offset:32768
	ds_read_b128 v[220:223], v159 offset:33792
	ds_read_b128 v[224:227], v159 offset:34816
	ds_read_b128 v[228:231], v159 offset:35840
	ds_read_b128 v[232:235], v159 offset:36864
	ds_read_b128 v[236:239], v159 offset:37888
	ds_read_b128 v[240:243], v159 offset:38912
	ds_read_b128 v[244:247], v159 offset:39936
	global_load_lds_dwordx4 v150, s[44:45]
	s_mov_b32 m0, s92
	s_nop 0
	global_load_lds_dwordx4 v154, s[44:45]
	s_waitcnt vmcnt(8)
	s_waitcnt lgkmcnt(0)
	s_barrier
	s_setprio 1
	s_waitcnt lgkmcnt(0)
	v_mfma_f32_16x16x32_bf16 v[124:127], v[162:165], v[216:219], v[124:127]
	v_mfma_f32_16x16x32_bf16 v[124:127], v[166:169], v[220:223], v[124:127]
	v_mfma_f32_16x16x32_bf16 v[120:123], v[196:199], v[220:223], v[120:123]
	v_mfma_f32_16x16x32_bf16 v[120:123], v[172:175], v[216:219], v[120:123]
	v_mfma_f32_16x16x32_bf16 v[104:107], v[172:175], v[224:227], v[104:107]
	v_mfma_f32_16x16x32_bf16 v[104:107], v[196:199], v[228:231], v[104:107]
	v_mfma_f32_16x16x32_bf16 v[108:111], v[166:169], v[228:231], v[108:111]
	v_mfma_f32_16x16x32_bf16 v[108:111], v[162:165], v[224:227], v[108:111]
	v_mfma_f32_16x16x32_bf16 v[92:95], v[162:165], v[232:235], v[92:95]
	v_mfma_f32_16x16x32_bf16 v[92:95], v[166:169], v[236:239], v[92:95]
	v_mfma_f32_16x16x32_bf16 v[88:91], v[196:199], v[236:239], v[88:91]
	v_mfma_f32_16x16x32_bf16 v[88:91], v[172:175], v[232:235], v[88:91]
	v_mfma_f32_16x16x32_bf16 v[72:75], v[172:175], v[240:243], v[72:75]
	v_mfma_f32_16x16x32_bf16 v[72:75], v[196:199], v[244:247], v[72:75]
	v_mfma_f32_16x16x32_bf16 v[76:79], v[166:169], v[244:247], v[76:79]
	v_mfma_f32_16x16x32_bf16 v[76:79], v[162:165], v[240:243], v[76:79]
	s_setprio 0
	s_setprio 1
	v_mfma_f32_16x16x32_bf16 v[116:119], v[200:203], v[216:219], v[116:119]
	v_mfma_f32_16x16x32_bf16 v[116:119], v[204:207], v[220:223], v[116:119]
	v_mfma_f32_16x16x32_bf16 v[112:115], v[212:215], v[220:223], v[112:115]
	v_mfma_f32_16x16x32_bf16 v[112:115], v[208:211], v[216:219], v[112:115]
	v_mfma_f32_16x16x32_bf16 v[96:99], v[208:211], v[224:227], v[96:99]
	v_mfma_f32_16x16x32_bf16 v[96:99], v[212:215], v[228:231], v[96:99]
	v_mfma_f32_16x16x32_bf16 v[100:103], v[204:207], v[228:231], v[100:103]
	v_mfma_f32_16x16x32_bf16 v[100:103], v[200:203], v[224:227], v[100:103]
	v_mfma_f32_16x16x32_bf16 v[84:87], v[200:203], v[232:235], v[84:87]
	v_mfma_f32_16x16x32_bf16 v[84:87], v[204:207], v[236:239], v[84:87]
	v_mfma_f32_16x16x32_bf16 v[80:83], v[212:215], v[236:239], v[80:83]
	v_mfma_f32_16x16x32_bf16 v[80:83], v[208:211], v[232:235], v[80:83]
	v_mfma_f32_16x16x32_bf16 v[64:67], v[208:211], v[240:243], v[64:67]
	v_mfma_f32_16x16x32_bf16 v[64:67], v[212:215], v[244:247], v[64:67]
	v_mfma_f32_16x16x32_bf16 v[68:71], v[204:207], v[244:247], v[68:71]
	v_mfma_f32_16x16x32_bf16 v[68:71], v[200:203], v[240:243], v[68:71]
	s_setprio 0
	s_barrier
	s_add_i32 s43, s43, s85
	s_mov_b32 m0, s43
	ds_read_b128 v[216:219], v159 offset:49152
	ds_read_b128 v[220:223], v159 offset:50176
	ds_read_b128 v[224:227], v159 offset:51200
	ds_read_b128 v[228:231], v159 offset:52224
	ds_read_b128 v[232:235], v159 offset:53248
	ds_read_b128 v[236:239], v159 offset:54272
	ds_read_b128 v[240:243], v159 offset:55296
	ds_read_b128 v[244:247], v159 offset:56320
	global_load_lds_dwordx4 v152, s[98:99]
	s_add_i32 m0, s43, 0x2000
	s_add_u32 s44, s76, 0x80080
	s_addc_u32 s45, s77, 0
	s_add_i32 s43, s46, s85
	global_load_lds_dwordx4 v156, s[98:99]
	s_mov_b32 m0, s43
	s_nop 0
	global_load_lds_dwordx4 v152, s[44:45]
	s_add_i32 m0, s43, 0x2000
	s_nop 0
	global_load_lds_dwordx4 v156, s[44:45]
	s_mov_b32 m0, s93
	s_nop 0
	global_load_lds_dwordx4 v150, s[100:101]
	s_mov_b32 m0, s94
	s_nop 0
	global_load_lds_dwordx4 v154, s[100:101]
	s_waitcnt vmcnt(8)
	s_waitcnt lgkmcnt(0)
	s_barrier
	s_setprio 1
	s_waitcnt lgkmcnt(0)
	v_mfma_f32_16x16x32_bf16 v[60:63], v[162:165], v[216:219], v[60:63]
	v_mfma_f32_16x16x32_bf16 v[60:63], v[166:169], v[220:223], v[60:63]
	v_mfma_f32_16x16x32_bf16 v[56:59], v[196:199], v[220:223], v[56:59]
	v_mfma_f32_16x16x32_bf16 v[56:59], v[172:175], v[216:219], v[56:59]
	v_mfma_f32_16x16x32_bf16 v[40:43], v[172:175], v[224:227], v[40:43]
	v_mfma_f32_16x16x32_bf16 v[40:43], v[196:199], v[228:231], v[40:43]
	v_mfma_f32_16x16x32_bf16 v[44:47], v[166:169], v[228:231], v[44:47]
	v_mfma_f32_16x16x32_bf16 v[44:47], v[162:165], v[224:227], v[44:47]
	v_mfma_f32_16x16x32_bf16 v[28:31], v[162:165], v[232:235], v[28:31]
	v_mfma_f32_16x16x32_bf16 v[28:31], v[166:169], v[236:239], v[28:31]
	v_mfma_f32_16x16x32_bf16 v[24:27], v[196:199], v[236:239], v[24:27]
	v_mfma_f32_16x16x32_bf16 v[24:27], v[172:175], v[232:235], v[24:27]
	v_mfma_f32_16x16x32_bf16 v[4:7], v[172:175], v[240:243], v[4:7]
	v_mfma_f32_16x16x32_bf16 v[4:7], v[196:199], v[244:247], v[4:7]
	v_mfma_f32_16x16x32_bf16 v[12:15], v[166:169], v[244:247], v[12:15]
	v_mfma_f32_16x16x32_bf16 v[12:15], v[162:165], v[240:243], v[12:15]
	s_setprio 0
	s_setprio 1
	v_mfma_f32_16x16x32_bf16 v[52:55], v[200:203], v[216:219], v[52:55]
	v_mfma_f32_16x16x32_bf16 v[52:55], v[204:207], v[220:223], v[52:55]
	v_mfma_f32_16x16x32_bf16 v[48:51], v[212:215], v[220:223], v[48:51]
	v_mfma_f32_16x16x32_bf16 v[48:51], v[208:211], v[216:219], v[48:51]
	v_mfma_f32_16x16x32_bf16 v[32:35], v[208:211], v[224:227], v[32:35]
	v_mfma_f32_16x16x32_bf16 v[32:35], v[212:215], v[228:231], v[32:35]
	v_mfma_f32_16x16x32_bf16 v[36:39], v[204:207], v[228:231], v[36:39]
	v_mfma_f32_16x16x32_bf16 v[36:39], v[200:203], v[224:227], v[36:39]
	v_mfma_f32_16x16x32_bf16 v[20:23], v[200:203], v[232:235], v[20:23]
	v_mfma_f32_16x16x32_bf16 v[20:23], v[204:207], v[236:239], v[20:23]
	v_mfma_f32_16x16x32_bf16 v[16:19], v[212:215], v[236:239], v[16:19]
	v_mfma_f32_16x16x32_bf16 v[16:19], v[208:211], v[232:235], v[16:19]
	v_mfma_f32_16x16x32_bf16 v[0:3], v[208:211], v[240:243], v[0:3]
	v_mfma_f32_16x16x32_bf16 v[0:3], v[212:215], v[244:247], v[0:3]
	v_mfma_f32_16x16x32_bf16 v[8:11], v[204:207], v[244:247], v[8:11]
	v_mfma_f32_16x16x32_bf16 v[8:11], v[200:203], v[240:243], v[8:11]
	s_setprio 0
	s_barrier
	s_add_i32 s42, s42, 2
	s_add_u32 s10, s10, 0x100
	s_addc_u32 s11, s11, 0
	s_add_u32 s40, s40, 0x100
	s_addc_u32 s41, s41, 0
	s_cmp_gt_u32 s42, 29
	s_cbranch_scc0 .LBB0_623
	s_and_b64 vcc, exec, s[66:67]
	s_cbranch_vccz .LBB0_628
	s_barrier
	v_lshl_add_u32 v162, s4, 8, v143
	s_cmp_lt_i32 s55, 10
	s_mov_b64 s[10:11], -1
	s_cbranch_scc1 .LBB0_629

; #define PG8_STAGE(bufoff, gbase, voff) do { _Pragma("unroll") for (int _i = 0; _i < 2; ++_i) \
;         __builtin_amdgcn_global_load_lds((const unsigned*)((const char*)(gbase) + (voff)[_i]), (PG8_LAS unsigned*)(lds + (bufoff) + ldsw + _i * 8192), 16, 0, 0); } while (0)
; #define PG8_LDA(dst, b, h) do { _Pragma("unroll") for (int m = 0; m < 4; ++m) _Pragma("unroll") for (int k = 0; k < 2; ++k) dst[m][k] = *(const PG8_LAS bf16x8*)(lds + PG8_SA(b, h) + aoff + m * 2048 + k * 1024); } while (0)
; #define PG8_LDB(dst, b, h) do { _Pragma("unroll") for (int n = 0; n < 2; ++n) _Pragma("unroll") for (int k = 0; k < 2; ++k) dst[n][k] = *(const PG8_LAS bf16x8*)(lds + PG8_SB(b, h) + boff + n * 2048 + k * 1024); } while (0)
; #define PG8_MMA(ai, bj, At, Bt) do { __builtin_amdgcn_s_setprio(1); _Pragma("unroll") for (int m = 0; m < 4; ++m) _Pragma("unroll") for (int n = 0; n < 2; ++n) _Pragma("unroll") for (int k = 0; k < 2; ++k) \
;         acc[ai][bj][m][n] = __builtin_amdgcn_mfma_f32_16x16x32_bf16(Bt[n][k], At[m][k], acc[ai][bj][m][n], 0, 0, 0); __builtin_amdgcn_s_setprio(0); } while (0)
; #define PG8_WAIT_V(n) asm volatile("s_waitcnt vmcnt(" #n ")" ::: "memory")
; #define PG8_BAR __builtin_amdgcn_s_barrier()
; template <class Epi, class Sched, bool ALIGN_EPI = false, bool SP2 = false>
; __device__ __forceinline__ void gemm_phase(PG8_LAS unsigned char* lds, const Gemm g, const Sched& S, const Epi& E) {
;     ...
;         for (int t = 0; t < nt; t += 2) {
;             const bool last = (t == nt - 2);
;             const char* a1 = cA + (size_t)(t + 1) * kstep;
;             const char* a2 = last ? nA : cA + (size_t)(t + 2) * kstep; const char* b2 = last ? nB : cB + (size_t)(t + 2) * kstep;
;             const char* a3 = a2 + kstep; const char* b3 = b2 + kstep;
;             if (last && has_next) S.a_ready(nxt);
;             if constexpr (SP2) {
;             PG8_LDB(B0, 0, 0); PG8_LDB(B1, 0, 1); PG8_SCHED; PG8_LDA(At, 0, 0); PG8_STAGE(PG8_SA(1, 1), a1 + hstep, voffA);
;             PG8_WAIT_V(8); PG8_WAIT_L(0); PG8_BAR; PG8_MMA(0, 0, At, B0); PG8_MMA(0, 1, At, B1); PG8_BAR; PG8_SCHED;
;             PG8_LDA(At, 0, 1); PG8_STAGE(PG8_SB(0, 0), b2, voffB); PG8_STAGE(PG8_SB(0, 1), b2 + hstep, voffB); PG8_STAGE(PG8_SA(0, 0), a2, voffA);
;             PG8_WAIT_V(8); PG8_WAIT_L(0); PG8_BAR; PG8_MMA(1, 0, At, B0); PG8_MMA(1, 1, At, B1); PG8_BAR; PG8_SCHED;
.LBB0_1056:
	ds_read_b128 v[128:131], v149
	ds_read_b128 v[132:135], v149 offset:1024
	ds_read_b128 v[172:175], v149 offset:2048
	ds_read_b128 v[188:191], v149 offset:3072
	ds_read_b128 v[192:195], v159
	ds_read_b128 v[196:199], v159 offset:1024
	ds_read_b128 v[200:203], v159 offset:2048
	ds_read_b128 v[204:207], v159 offset:3072
	s_add_u32 s40, s38, 0xfff80080
	s_addc_u32 s41, s39, -1
	s_cmp_eq_u32 s65, 28
	s_cselect_b32 s43, s27, s41
	s_cselect_b32 s42, s35, s40
	s_cselect_b32 s41, s25, s64
	s_cselect_b32 s40, s37, s63
	s_add_i32 m0, s46, 0xc000
	ds_read_b128 v[208:211], v163
	ds_read_b128 v[212:215], v163 offset:1024
	ds_read_b128 v[216:219], v163 offset:2048
	ds_read_b128 v[220:223], v163 offset:3072
	ds_read_b128 v[224:227], v163 offset:4096
	ds_read_b128 v[228:231], v163 offset:5120
	ds_read_b128 v[232:235], v163 offset:6144
	ds_read_b128 v[236:239], v163 offset:7168
	global_load_lds_dwordx4 v164, s[38:39]
	s_add_i32 m0, s46, 0xe000
	s_nop 0
	global_load_lds_dwordx4 v166, s[38:39]
	s_waitcnt vmcnt(8)
	s_waitcnt lgkmcnt(0)
	s_barrier
	s_setprio 1
	s_waitcnt lgkmcnt(0)
	v_mfma_f32_16x16x32_bf16 v[124:127], v[128:131], v[208:211], v[124:127]
	v_mfma_f32_16x16x32_bf16 v[124:127], v[132:135], v[212:215], v[124:127]
	v_mfma_f32_16x16x32_bf16 v[120:123], v[188:191], v[212:215], v[120:123]
	v_mfma_f32_16x16x32_bf16 v[120:123], v[172:175], v[208:211], v[120:123]
	v_mfma_f32_16x16x32_bf16 v[104:107], v[172:175], v[216:219], v[104:107]
	v_mfma_f32_16x16x32_bf16 v[104:107], v[188:191], v[220:223], v[104:107]
	v_mfma_f32_16x16x32_bf16 v[108:111], v[132:135], v[220:223], v[108:111]
	v_mfma_f32_16x16x32_bf16 v[108:111], v[128:131], v[216:219], v[108:111]
	v_mfma_f32_16x16x32_bf16 v[92:95], v[128:131], v[224:227], v[92:95]
	v_mfma_f32_16x16x32_bf16 v[92:95], v[132:135], v[228:231], v[92:95]
	v_mfma_f32_16x16x32_bf16 v[88:91], v[188:191], v[228:231], v[88:91]
	v_mfma_f32_16x16x32_bf16 v[88:91], v[172:175], v[224:227], v[88:91]
	v_mfma_f32_16x16x32_bf16 v[72:75], v[172:175], v[232:235], v[72:75]
	v_mfma_f32_16x16x32_bf16 v[72:75], v[188:191], v[236:239], v[72:75]
	v_mfma_f32_16x16x32_bf16 v[76:79], v[132:135], v[236:239], v[76:79]
	v_mfma_f32_16x16x32_bf16 v[76:79], v[128:131], v[232:235], v[76:79]
	s_setprio 0
	s_setprio 1
	v_mfma_f32_16x16x32_bf16 v[116:119], v[192:195], v[208:211], v[116:119]
	v_mfma_f32_16x16x32_bf16 v[116:119], v[196:199], v[212:215], v[116:119]
	v_mfma_f32_16x16x32_bf16 v[112:115], v[204:207], v[212:215], v[112:115]
	v_mfma_f32_16x16x32_bf16 v[112:115], v[200:203], v[208:211], v[112:115]
	v_mfma_f32_16x16x32_bf16 v[96:99], v[200:203], v[216:219], v[96:99]
	v_mfma_f32_16x16x32_bf16 v[96:99], v[204:207], v[220:223], v[96:99]
	v_mfma_f32_16x16x32_bf16 v[100:103], v[196:199], v[220:223], v[100:103]
	v_mfma_f32_16x16x32_bf16 v[100:103], v[192:195], v[216:219], v[100:103]
	v_mfma_f32_16x16x32_bf16 v[84:87], v[192:195], v[224:227], v[84:87]
	v_mfma_f32_16x16x32_bf16 v[84:87], v[196:199], v[228:231], v[84:87]
	v_mfma_f32_16x16x32_bf16 v[80:83], v[204:207], v[228:231], v[80:83]
	v_mfma_f32_16x16x32_bf16 v[80:83], v[200:203], v[224:227], v[80:83]
	v_mfma_f32_16x16x32_bf16 v[64:67], v[200:203], v[232:235], v[64:67]
	v_mfma_f32_16x16x32_bf16 v[64:67], v[204:207], v[236:239], v[64:67]
	v_mfma_f32_16x16x32_bf16 v[68:71], v[196:199], v[236:239], v[68:71]
	v_mfma_f32_16x16x32_bf16 v[68:71], v[192:195], v[232:235], v[68:71]
	s_setprio 0
	s_barrier
	s_add_u32 s98, s40, 0x80
	s_addc_u32 s99, s41, 0
	s_add_u32 s100, s42, 0x80
	s_addc_u32 s101, s43, 0
	s_add_i32 s66, s56, s45
	s_mov_b32 m0, s66
	ds_read_b128 v[208:211], v163 offset:16384
	ds_read_b128 v[212:215], v163 offset:17408
	ds_read_b128 v[216:219], v163 offset:18432
	ds_read_b128 v[220:223], v163 offset:19456
	ds_read_b128 v[224:227], v163 offset:20480
	ds_read_b128 v[228:231], v163 offset:21504
	ds_read_b128 v[232:235], v163 offset:22528
	ds_read_b128 v[236:239], v163 offset:23552
	global_load_lds_dwordx4 v152, s[40:41]
	s_add_i32 m0, s66, 0x2000
	s_add_u32 s66, s40, 0x80000
	s_addc_u32 s67, s41, 0
	s_add_i32 s68, s57, s45
	global_load_lds_dwordx4 v156, s[40:41]
	s_mov_b32 m0, s68
	s_nop 0
	global_load_lds_dwordx4 v152, s[66:67]
	s_add_i32 m0, s68, 0x2000
	s_nop 0
	global_load_lds_dwordx4 v156, s[66:67]
	s_mov_b32 m0, s46
	s_nop 0
	global_load_lds_dwordx4 v150, s[42:43]
	s_mov_b32 m0, s47
	s_nop 0
	global_load_lds_dwordx4 v154, s[42:43]
	s_waitcnt vmcnt(8)
	s_waitcnt lgkmcnt(0)
	s_barrier
	s_setprio 1
	s_waitcnt lgkmcnt(0)
	v_mfma_f32_16x16x32_bf16 v[60:63], v[128:131], v[208:211], v[60:63]
	v_mfma_f32_16x16x32_bf16 v[60:63], v[132:135], v[212:215], v[60:63]
	v_mfma_f32_16x16x32_bf16 v[56:59], v[188:191], v[212:215], v[56:59]
	v_mfma_f32_16x16x32_bf16 v[56:59], v[172:175], v[208:211], v[56:59]
	v_mfma_f32_16x16x32_bf16 v[40:43], v[172:175], v[216:219], v[40:43]
	v_mfma_f32_16x16x32_bf16 v[40:43], v[188:191], v[220:223], v[40:43]
	v_mfma_f32_16x16x32_bf16 v[44:47], v[132:135], v[220:223], v[44:47]
	v_mfma_f32_16x16x32_bf16 v[44:47], v[128:131], v[216:219], v[44:47]
	v_mfma_f32_16x16x32_bf16 v[28:31], v[128:131], v[224:227], v[28:31]
	v_mfma_f32_16x16x32_bf16 v[28:31], v[132:135], v[228:231], v[28:31]
	v_mfma_f32_16x16x32_bf16 v[24:27], v[188:191], v[228:231], v[24:27]
	v_mfma_f32_16x16x32_bf16 v[24:27], v[172:175], v[224:227], v[24:27]
	v_mfma_f32_16x16x32_bf16 v[8:11], v[172:175], v[232:235], v[8:11]
	v_mfma_f32_16x16x32_bf16 v[8:11], v[188:191], v[236:239], v[8:11]
	v_mfma_f32_16x16x32_bf16 v[12:15], v[132:135], v[236:239], v[12:15]
	v_mfma_f32_16x16x32_bf16 v[12:15], v[128:131], v[232:235], v[12:15]
	s_setprio 0
	s_setprio 1
	v_mfma_f32_16x16x32_bf16 v[52:55], v[192:195], v[208:211], v[52:55]
	v_mfma_f32_16x16x32_bf16 v[52:55], v[196:199], v[212:215], v[52:55]
	v_mfma_f32_16x16x32_bf16 v[48:51], v[204:207], v[212:215], v[48:51]
	v_mfma_f32_16x16x32_bf16 v[48:51], v[200:203], v[208:211], v[48:51]
	v_mfma_f32_16x16x32_bf16 v[32:35], v[200:203], v[216:219], v[32:35]
	v_mfma_f32_16x16x32_bf16 v[32:35], v[204:207], v[220:223], v[32:35]
	v_mfma_f32_16x16x32_bf16 v[36:39], v[196:199], v[220:223], v[36:39]
	v_mfma_f32_16x16x32_bf16 v[36:39], v[192:195], v[216:219], v[36:39]
	v_mfma_f32_16x16x32_bf16 v[20:23], v[192:195], v[224:227], v[20:23]
	v_mfma_f32_16x16x32_bf16 v[20:23], v[196:199], v[228:231], v[20:23]
	v_mfma_f32_16x16x32_bf16 v[16:19], v[204:207], v[228:231], v[16:19]
	v_mfma_f32_16x16x32_bf16 v[16:19], v[200:203], v[224:227], v[16:19]
	v_mfma_f32_16x16x32_bf16 v[0:3], v[200:203], v[232:235], v[0:3]
	v_mfma_f32_16x16x32_bf16 v[0:3], v[204:207], v[236:239], v[0:3]
	v_mfma_f32_16x16x32_bf16 v[4:7], v[196:199], v[236:239], v[4:7]
	v_mfma_f32_16x16x32_bf16 v[4:7], v[192:195], v[232:235], v[4:7]
	s_setprio 0
	s_barrier
; #define PG8_STAGE(bufoff, gbase, voff) do { _Pragma("unroll") for (int _i = 0; _i < 2; ++_i) \
;         __builtin_amdgcn_global_load_lds((const unsigned*)((const char*)(gbase) + (voff)[_i]), (PG8_LAS unsigned*)(lds + (bufoff) + ldsw + _i * 8192), 16, 0, 0); } while (0)
; #define PG8_LDA(dst, b, h) do { _Pragma("unroll") for (int m = 0; m < 4; ++m) _Pragma("unroll") for (int k = 0; k < 2; ++k) dst[m][k] = *(const PG8_LAS bf16x8*)(lds + PG8_SA(b, h) + aoff + m * 2048 + k * 1024); } while (0)
; #define PG8_LDB(dst, b, h) do { _Pragma("unroll") for (int n = 0; n < 2; ++n) _Pragma("unroll") for (int k = 0; k < 2; ++k) dst[n][k] = *(const PG8_LAS bf16x8*)(lds + PG8_SB(b, h) + boff + n * 2048 + k * 1024); } while (0)
; #define PG8_MMA(ai, bj, At, Bt) do { __builtin_amdgcn_s_setprio(1); _Pragma("unroll") for (int m = 0; m < 4; ++m) _Pragma("unroll") for (int n = 0; n < 2; ++n) _Pragma("unroll") for (int k = 0; k < 2; ++k) \
;         acc[ai][bj][m][n] = __builtin_amdgcn_mfma_f32_16x16x32_bf16(Bt[n][k], At[m][k], acc[ai][bj][m][n], 0, 0, 0); __builtin_amdgcn_s_setprio(0); } while (0)
; #define PG8_WAIT_V(n) asm volatile("s_waitcnt vmcnt(" #n ")" ::: "memory")
; #define PG8_WAIT_L(n) asm volatile("s_waitcnt lgkmcnt(" #n ")" ::: "memory")
; #define PG8_BAR __builtin_amdgcn_s_barrier()
; #define PG8_SCHED __builtin_amdgcn_sched_barrier(0)
; template <class Epi, class Sched, bool ALIGN_EPI = false, bool SP2 = false>
; __device__ __forceinline__ void gemm_phase(PG8_LAS unsigned char* lds, const Gemm g, const Sched& S, const Epi& E) {
;     ...
;             PG8_LDB(B0, 1, 0); PG8_LDB(B1, 1, 1); PG8_SCHED; PG8_LDA(At, 1, 0); PG8_STAGE(PG8_SA(0, 1), a2 + hstep, voffA);
;             PG8_WAIT_V(8); PG8_WAIT_L(0); PG8_BAR; PG8_MMA(0, 0, At, B0); PG8_MMA(0, 1, At, B1); PG8_BAR; PG8_SCHED;
;             PG8_LDA(At, 1, 1); PG8_STAGE(PG8_SB(1, 0), b3, voffB); PG8_STAGE(PG8_SB(1, 1), b3 + hstep, voffB); PG8_STAGE(PG8_SA(1, 0), a3, voffA);
;             PG8_WAIT_V(8); PG8_WAIT_L(0); PG8_BAR; PG8_MMA(1, 0, At, B0); PG8_MMA(1, 1, At, B1); PG8_BAR; PG8_SCHED;
;     ...
;         if constexpr (ALIGN_EPI) { if (wr == 0) PG8_BAR; }
	s_add_i32 s66, 0, 0x18000
	v_add_u32_e32 v160, s66, v145
	s_add_i32 s67, 0, 0x1c000
	ds_read_b128 v[128:131], v160
	ds_read_b128 v[132:135], v160 offset:1024
	ds_read_b128 v[172:175], v160 offset:2048
	ds_read_b128 v[188:191], v160 offset:3072
	v_add_u32_e32 v160, s67, v145
	ds_read_b128 v[192:195], v160
	ds_read_b128 v[196:199], v160 offset:1024
	ds_read_b128 v[200:203], v160 offset:2048
	ds_read_b128 v[204:207], v160 offset:3072
	s_add_u32 s42, s42, 0x80000
	s_addc_u32 s43, s43, 0
	s_mov_b32 m0, s48
	ds_read_b128 v[208:211], v163 offset:32768
	ds_read_b128 v[212:215], v163 offset:33792
	ds_read_b128 v[216:219], v163 offset:34816
	ds_read_b128 v[220:223], v163 offset:35840
	ds_read_b128 v[224:227], v163 offset:36864
	ds_read_b128 v[228:231], v163 offset:37888
	ds_read_b128 v[232:235], v163 offset:38912
	ds_read_b128 v[236:239], v163 offset:39936
	global_load_lds_dwordx4 v150, s[42:43]
	s_mov_b32 m0, s49
	s_nop 0
	global_load_lds_dwordx4 v154, s[42:43]
	s_waitcnt vmcnt(8)
	s_waitcnt lgkmcnt(0)
	s_barrier
	s_setprio 1
	s_waitcnt lgkmcnt(0)
	v_mfma_f32_16x16x32_bf16 v[124:127], v[128:131], v[208:211], v[124:127]
	v_mfma_f32_16x16x32_bf16 v[124:127], v[132:135], v[212:215], v[124:127]
	v_mfma_f32_16x16x32_bf16 v[120:123], v[188:191], v[212:215], v[120:123]
	v_mfma_f32_16x16x32_bf16 v[120:123], v[172:175], v[208:211], v[120:123]
	v_mfma_f32_16x16x32_bf16 v[104:107], v[172:175], v[216:219], v[104:107]
	v_mfma_f32_16x16x32_bf16 v[104:107], v[188:191], v[220:223], v[104:107]
	v_mfma_f32_16x16x32_bf16 v[108:111], v[132:135], v[220:223], v[108:111]
	v_mfma_f32_16x16x32_bf16 v[108:111], v[128:131], v[216:219], v[108:111]
	v_mfma_f32_16x16x32_bf16 v[92:95], v[128:131], v[224:227], v[92:95]
	v_mfma_f32_16x16x32_bf16 v[92:95], v[132:135], v[228:231], v[92:95]
	v_mfma_f32_16x16x32_bf16 v[88:91], v[188:191], v[228:231], v[88:91]
	v_mfma_f32_16x16x32_bf16 v[88:91], v[172:175], v[224:227], v[88:91]
	v_mfma_f32_16x16x32_bf16 v[72:75], v[172:175], v[232:235], v[72:75]
	v_mfma_f32_16x16x32_bf16 v[72:75], v[188:191], v[236:239], v[72:75]
	v_mfma_f32_16x16x32_bf16 v[76:79], v[132:135], v[236:239], v[76:79]
	v_mfma_f32_16x16x32_bf16 v[76:79], v[128:131], v[232:235], v[76:79]
	s_setprio 0
	s_setprio 1
	v_mfma_f32_16x16x32_bf16 v[116:119], v[192:195], v[208:211], v[116:119]
	v_mfma_f32_16x16x32_bf16 v[116:119], v[196:199], v[212:215], v[116:119]
	v_mfma_f32_16x16x32_bf16 v[112:115], v[204:207], v[212:215], v[112:115]
	v_mfma_f32_16x16x32_bf16 v[112:115], v[200:203], v[208:211], v[112:115]
	v_mfma_f32_16x16x32_bf16 v[96:99], v[200:203], v[216:219], v[96:99]
	v_mfma_f32_16x16x32_bf16 v[96:99], v[204:207], v[220:223], v[96:99]
	v_mfma_f32_16x16x32_bf16 v[100:103], v[196:199], v[220:223], v[100:103]
	v_mfma_f32_16x16x32_bf16 v[100:103], v[192:195], v[216:219], v[100:103]
	v_mfma_f32_16x16x32_bf16 v[84:87], v[192:195], v[224:227], v[84:87]
	v_mfma_f32_16x16x32_bf16 v[84:87], v[196:199], v[228:231], v[84:87]
	v_mfma_f32_16x16x32_bf16 v[80:83], v[204:207], v[228:231], v[80:83]
	v_mfma_f32_16x16x32_bf16 v[80:83], v[200:203], v[224:227], v[80:83]
	v_mfma_f32_16x16x32_bf16 v[64:67], v[200:203], v[232:235], v[64:67]
	v_mfma_f32_16x16x32_bf16 v[64:67], v[204:207], v[236:239], v[64:67]
	v_mfma_f32_16x16x32_bf16 v[68:71], v[196:199], v[236:239], v[68:71]
	v_mfma_f32_16x16x32_bf16 v[68:71], v[192:195], v[232:235], v[68:71]
	s_setprio 0
	s_barrier
	s_add_i32 s42, s66, s45
	s_mov_b32 m0, s42
	ds_read_b128 v[208:211], v163 offset:49152
	ds_read_b128 v[212:215], v163 offset:50176
	ds_read_b128 v[216:219], v163 offset:51200
	ds_read_b128 v[220:223], v163 offset:52224
	ds_read_b128 v[224:227], v163 offset:53248
	ds_read_b128 v[228:231], v163 offset:54272
	ds_read_b128 v[232:235], v163 offset:55296
	ds_read_b128 v[236:239], v163 offset:56320
	global_load_lds_dwordx4 v152, s[98:99]
	s_add_i32 m0, s42, 0x2000
	s_add_u32 s40, s40, 0x80080
	s_addc_u32 s41, s41, 0
	s_add_i32 s42, s67, s45
	global_load_lds_dwordx4 v156, s[98:99]
	s_mov_b32 m0, s42
	s_nop 0
	global_load_lds_dwordx4 v152, s[40:41]
	s_add_i32 m0, s42, 0x2000
	s_nop 0
	global_load_lds_dwordx4 v156, s[40:41]
	s_mov_b32 m0, s51
	s_nop 0
	global_load_lds_dwordx4 v150, s[100:101]
	s_mov_b32 m0, s52
	s_nop 0
	global_load_lds_dwordx4 v154, s[100:101]
	s_waitcnt vmcnt(8)
	s_waitcnt lgkmcnt(0)
	s_barrier
	s_setprio 1
	s_waitcnt lgkmcnt(0)
	v_mfma_f32_16x16x32_bf16 v[60:63], v[128:131], v[208:211], v[60:63]
	v_mfma_f32_16x16x32_bf16 v[60:63], v[132:135], v[212:215], v[60:63]
	v_mfma_f32_16x16x32_bf16 v[56:59], v[188:191], v[212:215], v[56:59]
	v_mfma_f32_16x16x32_bf16 v[56:59], v[172:175], v[208:211], v[56:59]
	v_mfma_f32_16x16x32_bf16 v[40:43], v[172:175], v[216:219], v[40:43]
	v_mfma_f32_16x16x32_bf16 v[40:43], v[188:191], v[220:223], v[40:43]
	v_mfma_f32_16x16x32_bf16 v[44:47], v[132:135], v[220:223], v[44:47]
	v_mfma_f32_16x16x32_bf16 v[44:47], v[128:131], v[216:219], v[44:47]
	v_mfma_f32_16x16x32_bf16 v[28:31], v[128:131], v[224:227], v[28:31]
	v_mfma_f32_16x16x32_bf16 v[28:31], v[132:135], v[228:231], v[28:31]
	v_mfma_f32_16x16x32_bf16 v[24:27], v[188:191], v[228:231], v[24:27]
	v_mfma_f32_16x16x32_bf16 v[24:27], v[172:175], v[224:227], v[24:27]
	v_mfma_f32_16x16x32_bf16 v[8:11], v[172:175], v[232:235], v[8:11]
	v_mfma_f32_16x16x32_bf16 v[8:11], v[188:191], v[236:239], v[8:11]
	v_mfma_f32_16x16x32_bf16 v[12:15], v[132:135], v[236:239], v[12:15]
	v_mfma_f32_16x16x32_bf16 v[12:15], v[128:131], v[232:235], v[12:15]
	s_setprio 0
	s_setprio 1
	v_mfma_f32_16x16x32_bf16 v[52:55], v[192:195], v[208:211], v[52:55]
	v_mfma_f32_16x16x32_bf16 v[52:55], v[196:199], v[212:215], v[52:55]
	v_mfma_f32_16x16x32_bf16 v[48:51], v[204:207], v[212:215], v[48:51]
	v_mfma_f32_16x16x32_bf16 v[48:51], v[200:203], v[208:211], v[48:51]
	v_mfma_f32_16x16x32_bf16 v[32:35], v[200:203], v[216:219], v[32:35]
	v_mfma_f32_16x16x32_bf16 v[32:35], v[204:207], v[220:223], v[32:35]
	v_mfma_f32_16x16x32_bf16 v[36:39], v[196:199], v[220:223], v[36:39]
	v_mfma_f32_16x16x32_bf16 v[36:39], v[192:195], v[216:219], v[36:39]
	v_mfma_f32_16x16x32_bf16 v[20:23], v[192:195], v[224:227], v[20:23]
	v_mfma_f32_16x16x32_bf16 v[20:23], v[196:199], v[228:231], v[20:23]
	v_mfma_f32_16x16x32_bf16 v[16:19], v[204:207], v[228:231], v[16:19]
	v_mfma_f32_16x16x32_bf16 v[16:19], v[200:203], v[224:227], v[16:19]
	v_mfma_f32_16x16x32_bf16 v[0:3], v[200:203], v[232:235], v[0:3]
	v_mfma_f32_16x16x32_bf16 v[0:3], v[204:207], v[236:239], v[0:3]
	v_mfma_f32_16x16x32_bf16 v[4:7], v[196:199], v[236:239], v[4:7]
	v_mfma_f32_16x16x32_bf16 v[4:7], v[192:195], v[232:235], v[4:7]
	s_setprio 0
	s_barrier
	s_add_i32 s65, s65, 2
	s_add_u32 s38, s38, 0x100
	s_addc_u32 s39, s39, 0
	s_add_u32 s63, s63, 0x100
	s_addc_u32 s64, s64, 0
	s_cmp_gt_u32 s65, 29
	s_cbranch_scc0 .LBB0_1056
	s_and_b64 vcc, exec, s[22:23]
	s_cbranch_vccz .LBB0_1059
	s_barrier

; #define PG8_STAGE(bufoff, gbase, voff) do { _Pragma("unroll") for (int _i = 0; _i < 2; ++_i) \
;         __builtin_amdgcn_global_load_lds((const unsigned*)((const char*)(gbase) + (voff)[_i]), (PG8_LAS unsigned*)(lds + (bufoff) + ldsw + _i * 8192), 16, 0, 0); } while (0)
; #define PG8_LDA(dst, b, h) do { _Pragma("unroll") for (int m = 0; m < 4; ++m) _Pragma("unroll") for (int k = 0; k < 2; ++k) dst[m][k] = *(const PG8_LAS bf16x8*)(lds + PG8_SA(b, h) + aoff + m * 2048 + k * 1024); } while (0)
; #define PG8_LDB(dst, b, h) do { _Pragma("unroll") for (int n = 0; n < 2; ++n) _Pragma("unroll") for (int k = 0; k < 2; ++k) dst[n][k] = *(const PG8_LAS bf16x8*)(lds + PG8_SB(b, h) + boff + n * 2048 + k * 1024); } while (0)
; #define PG8_MMA(ai, bj, At, Bt) do { __builtin_amdgcn_s_setprio(1); _Pragma("unroll") for (int m = 0; m < 4; ++m) _Pragma("unroll") for (int n = 0; n < 2; ++n) _Pragma("unroll") for (int k = 0; k < 2; ++k) \
;         acc[ai][bj][m][n] = __builtin_amdgcn_mfma_f32_16x16x32_bf16(Bt[n][k], At[m][k], acc[ai][bj][m][n], 0, 0, 0); __builtin_amdgcn_s_setprio(0); } while (0)
; #define PG8_WAIT_V(n) asm volatile("s_waitcnt vmcnt(" #n ")" ::: "memory")
; #define PG8_BAR __builtin_amdgcn_s_barrier()
; template <class Epi, class Sched, bool ALIGN_EPI = false, bool SP2 = false>
; __device__ __forceinline__ void gemm_phase(PG8_LAS unsigned char* lds, const Gemm g, const Sched& S, const Epi& E) {
;     ...
;         for (int t = 0; t < nt; t += 2) {
;             const bool last = (t == nt - 2);
;             const char* a1 = cA + (size_t)(t + 1) * kstep;
;             const char* a2 = last ? nA : cA + (size_t)(t + 2) * kstep; const char* b2 = last ? nB : cB + (size_t)(t + 2) * kstep;
;             const char* a3 = a2 + kstep; const char* b3 = b2 + kstep;
;             if (last && has_next) S.a_ready(nxt);
;             if constexpr (SP2) {
;             PG8_LDB(B0, 0, 0); PG8_LDB(B1, 0, 1); PG8_SCHED; PG8_LDA(At, 0, 0); PG8_STAGE(PG8_SA(1, 1), a1 + hstep, voffA);
;             PG8_WAIT_V(8); PG8_WAIT_L(0); PG8_BAR; PG8_MMA(0, 0, At, B0); PG8_MMA(0, 1, At, B1); PG8_BAR; PG8_SCHED;
;             PG8_LDA(At, 0, 1); PG8_STAGE(PG8_SB(0, 0), b2, voffB); PG8_STAGE(PG8_SB(0, 1), b2 + hstep, voffB); PG8_STAGE(PG8_SA(0, 0), a2, voffA);
;             PG8_WAIT_V(8); PG8_WAIT_L(0); PG8_BAR; PG8_MMA(1, 0, At, B0); PG8_MMA(1, 1, At, B1); PG8_BAR; PG8_SCHED;
.LBB0_1279:
	ds_read_b128 v[166:169], v149
	ds_read_b128 v[170:173], v149 offset:1024
	ds_read_b128 v[174:177], v149 offset:2048
	ds_read_b128 v[186:189], v149 offset:3072
	ds_read_b128 v[190:193], v159
	ds_read_b128 v[194:197], v159 offset:1024
	ds_read_b128 v[198:201], v159 offset:2048
	ds_read_b128 v[202:205], v159 offset:3072
	s_add_u32 s28, s26, 0xfff80080
	s_addc_u32 s29, s27, -1
	s_cmp_eq_u32 s54, 28
	s_cselect_b32 s31, s21, s29
	s_cselect_b32 s30, s50, s28
	s_cselect_b32 s29, s19, s53
	s_cselect_b32 s28, s51, s52
	s_add_i32 m0, s37, 0xc000
	ds_read_b128 v[206:209], v162
	ds_read_b128 v[210:213], v162 offset:1024
	ds_read_b128 v[214:217], v162 offset:2048
	ds_read_b128 v[218:221], v162 offset:3072
	ds_read_b128 v[222:225], v162 offset:4096
	ds_read_b128 v[226:229], v162 offset:5120
	ds_read_b128 v[230:233], v162 offset:6144
	ds_read_b128 v[234:237], v162 offset:7168
	global_load_lds_dwordx4 v128, s[26:27]
	s_add_i32 m0, s37, 0xe000
	s_nop 0
	global_load_lds_dwordx4 v130, s[26:27]
	s_waitcnt vmcnt(8)
	s_waitcnt lgkmcnt(0)
	s_barrier
	s_setprio 1
	s_waitcnt lgkmcnt(0)
	v_mfma_f32_16x16x32_bf16 v[124:127], v[166:169], v[206:209], v[124:127]
	v_mfma_f32_16x16x32_bf16 v[124:127], v[170:173], v[210:213], v[124:127]
	v_mfma_f32_16x16x32_bf16 v[120:123], v[186:189], v[210:213], v[120:123]
	v_mfma_f32_16x16x32_bf16 v[120:123], v[174:177], v[206:209], v[120:123]
	v_mfma_f32_16x16x32_bf16 v[104:107], v[174:177], v[214:217], v[104:107]
	v_mfma_f32_16x16x32_bf16 v[104:107], v[186:189], v[218:221], v[104:107]
	v_mfma_f32_16x16x32_bf16 v[108:111], v[170:173], v[218:221], v[108:111]
	v_mfma_f32_16x16x32_bf16 v[108:111], v[166:169], v[214:217], v[108:111]
	v_mfma_f32_16x16x32_bf16 v[92:95], v[166:169], v[222:225], v[92:95]
	v_mfma_f32_16x16x32_bf16 v[92:95], v[170:173], v[226:229], v[92:95]
	v_mfma_f32_16x16x32_bf16 v[88:91], v[186:189], v[226:229], v[88:91]
	v_mfma_f32_16x16x32_bf16 v[88:91], v[174:177], v[222:225], v[88:91]
	v_mfma_f32_16x16x32_bf16 v[72:75], v[174:177], v[230:233], v[72:75]
	v_mfma_f32_16x16x32_bf16 v[72:75], v[186:189], v[234:237], v[72:75]
	v_mfma_f32_16x16x32_bf16 v[76:79], v[170:173], v[234:237], v[76:79]
	v_mfma_f32_16x16x32_bf16 v[76:79], v[166:169], v[230:233], v[76:79]
	s_setprio 0
	s_setprio 1
	v_mfma_f32_16x16x32_bf16 v[116:119], v[190:193], v[206:209], v[116:119]
	v_mfma_f32_16x16x32_bf16 v[116:119], v[194:197], v[210:213], v[116:119]
	v_mfma_f32_16x16x32_bf16 v[112:115], v[202:205], v[210:213], v[112:115]
	v_mfma_f32_16x16x32_bf16 v[112:115], v[198:201], v[206:209], v[112:115]
	v_mfma_f32_16x16x32_bf16 v[96:99], v[198:201], v[214:217], v[96:99]
	v_mfma_f32_16x16x32_bf16 v[96:99], v[202:205], v[218:221], v[96:99]
	v_mfma_f32_16x16x32_bf16 v[100:103], v[194:197], v[218:221], v[100:103]
	v_mfma_f32_16x16x32_bf16 v[100:103], v[190:193], v[214:217], v[100:103]
	v_mfma_f32_16x16x32_bf16 v[84:87], v[190:193], v[222:225], v[84:87]
	v_mfma_f32_16x16x32_bf16 v[84:87], v[194:197], v[226:229], v[84:87]
	v_mfma_f32_16x16x32_bf16 v[80:83], v[202:205], v[226:229], v[80:83]
	v_mfma_f32_16x16x32_bf16 v[80:83], v[198:201], v[222:225], v[80:83]
	v_mfma_f32_16x16x32_bf16 v[64:67], v[198:201], v[230:233], v[64:67]
	v_mfma_f32_16x16x32_bf16 v[64:67], v[202:205], v[234:237], v[64:67]
	v_mfma_f32_16x16x32_bf16 v[68:71], v[194:197], v[234:237], v[68:71]
	v_mfma_f32_16x16x32_bf16 v[68:71], v[190:193], v[230:233], v[68:71]
	s_setprio 0
	s_barrier
	s_add_u32 s98, s28, 0x80
	s_addc_u32 s99, s29, 0
	s_add_u32 s100, s30, 0x80
	s_addc_u32 s101, s31, 0
	s_add_i32 s55, s46, s36
	s_mov_b32 m0, s55
	ds_read_b128 v[206:209], v162 offset:16384
	ds_read_b128 v[210:213], v162 offset:17408
	ds_read_b128 v[214:217], v162 offset:18432
	ds_read_b128 v[218:221], v162 offset:19456
	ds_read_b128 v[222:225], v162 offset:20480
	ds_read_b128 v[226:229], v162 offset:21504
	ds_read_b128 v[230:233], v162 offset:22528
	ds_read_b128 v[234:237], v162 offset:23552
	global_load_lds_dwordx4 v152, s[28:29]
	s_add_i32 m0, s55, 0x2000
	s_add_u32 s56, s28, 0x80000
	s_addc_u32 s57, s29, 0
	s_add_i32 s55, s47, s36
	global_load_lds_dwordx4 v156, s[28:29]
	s_mov_b32 m0, s55
	s_nop 0
	global_load_lds_dwordx4 v152, s[56:57]
	s_add_i32 m0, s55, 0x2000
	s_nop 0
	global_load_lds_dwordx4 v156, s[56:57]
	s_mov_b32 m0, s37
	s_nop 0
	global_load_lds_dwordx4 v150, s[30:31]
	s_mov_b32 m0, s38
	s_nop 0
	global_load_lds_dwordx4 v154, s[30:31]
	s_waitcnt vmcnt(8)
	s_waitcnt lgkmcnt(0)
	s_barrier
	s_setprio 1
	s_waitcnt lgkmcnt(0)
	v_mfma_f32_16x16x32_bf16 v[60:63], v[166:169], v[206:209], v[60:63]
	v_mfma_f32_16x16x32_bf16 v[60:63], v[170:173], v[210:213], v[60:63]
	v_mfma_f32_16x16x32_bf16 v[56:59], v[186:189], v[210:213], v[56:59]
	v_mfma_f32_16x16x32_bf16 v[56:59], v[174:177], v[206:209], v[56:59]
	v_mfma_f32_16x16x32_bf16 v[40:43], v[174:177], v[214:217], v[40:43]
	v_mfma_f32_16x16x32_bf16 v[40:43], v[186:189], v[218:221], v[40:43]
	v_mfma_f32_16x16x32_bf16 v[44:47], v[170:173], v[218:221], v[44:47]
	v_mfma_f32_16x16x32_bf16 v[44:47], v[166:169], v[214:217], v[44:47]
	v_mfma_f32_16x16x32_bf16 v[28:31], v[166:169], v[222:225], v[28:31]
	v_mfma_f32_16x16x32_bf16 v[28:31], v[170:173], v[226:229], v[28:31]
	v_mfma_f32_16x16x32_bf16 v[24:27], v[186:189], v[226:229], v[24:27]
	v_mfma_f32_16x16x32_bf16 v[24:27], v[174:177], v[222:225], v[24:27]
	v_mfma_f32_16x16x32_bf16 v[8:11], v[174:177], v[230:233], v[8:11]
	v_mfma_f32_16x16x32_bf16 v[8:11], v[186:189], v[234:237], v[8:11]
	v_mfma_f32_16x16x32_bf16 v[12:15], v[170:173], v[234:237], v[12:15]
	v_mfma_f32_16x16x32_bf16 v[12:15], v[166:169], v[230:233], v[12:15]
	s_setprio 0
	s_setprio 1
	v_mfma_f32_16x16x32_bf16 v[52:55], v[190:193], v[206:209], v[52:55]
	v_mfma_f32_16x16x32_bf16 v[52:55], v[194:197], v[210:213], v[52:55]
	v_mfma_f32_16x16x32_bf16 v[48:51], v[202:205], v[210:213], v[48:51]
	v_mfma_f32_16x16x32_bf16 v[48:51], v[198:201], v[206:209], v[48:51]
	v_mfma_f32_16x16x32_bf16 v[32:35], v[198:201], v[214:217], v[32:35]
	v_mfma_f32_16x16x32_bf16 v[32:35], v[202:205], v[218:221], v[32:35]
	v_mfma_f32_16x16x32_bf16 v[36:39], v[194:197], v[218:221], v[36:39]
	v_mfma_f32_16x16x32_bf16 v[36:39], v[190:193], v[214:217], v[36:39]
	v_mfma_f32_16x16x32_bf16 v[20:23], v[190:193], v[222:225], v[20:23]
	v_mfma_f32_16x16x32_bf16 v[20:23], v[194:197], v[226:229], v[20:23]
	v_mfma_f32_16x16x32_bf16 v[16:19], v[202:205], v[226:229], v[16:19]
	v_mfma_f32_16x16x32_bf16 v[16:19], v[198:201], v[222:225], v[16:19]
	v_mfma_f32_16x16x32_bf16 v[0:3], v[198:201], v[230:233], v[0:3]
	v_mfma_f32_16x16x32_bf16 v[0:3], v[202:205], v[234:237], v[0:3]
	v_mfma_f32_16x16x32_bf16 v[4:7], v[194:197], v[234:237], v[4:7]
	v_mfma_f32_16x16x32_bf16 v[4:7], v[190:193], v[230:233], v[4:7]
	s_setprio 0
	s_barrier
; #define PG8_STAGE(bufoff, gbase, voff) do { _Pragma("unroll") for (int _i = 0; _i < 2; ++_i) \
;         __builtin_amdgcn_global_load_lds((const unsigned*)((const char*)(gbase) + (voff)[_i]), (PG8_LAS unsigned*)(lds + (bufoff) + ldsw + _i * 8192), 16, 0, 0); } while (0)
; #define PG8_LDA(dst, b, h) do { _Pragma("unroll") for (int m = 0; m < 4; ++m) _Pragma("unroll") for (int k = 0; k < 2; ++k) dst[m][k] = *(const PG8_LAS bf16x8*)(lds + PG8_SA(b, h) + aoff + m * 2048 + k * 1024); } while (0)
; #define PG8_LDB(dst, b, h) do { _Pragma("unroll") for (int n = 0; n < 2; ++n) _Pragma("unroll") for (int k = 0; k < 2; ++k) dst[n][k] = *(const PG8_LAS bf16x8*)(lds + PG8_SB(b, h) + boff + n * 2048 + k * 1024); } while (0)
; #define PG8_MMA(ai, bj, At, Bt) do { __builtin_amdgcn_s_setprio(1); _Pragma("unroll") for (int m = 0; m < 4; ++m) _Pragma("unroll") for (int n = 0; n < 2; ++n) _Pragma("unroll") for (int k = 0; k < 2; ++k) \
;         acc[ai][bj][m][n] = __builtin_amdgcn_mfma_f32_16x16x32_bf16(Bt[n][k], At[m][k], acc[ai][bj][m][n], 0, 0, 0); __builtin_amdgcn_s_setprio(0); } while (0)
; #define PG8_WAIT_V(n) asm volatile("s_waitcnt vmcnt(" #n ")" ::: "memory")
; #define PG8_WAIT_L(n) asm volatile("s_waitcnt lgkmcnt(" #n ")" ::: "memory")
; #define PG8_BAR __builtin_amdgcn_s_barrier()
; #define PG8_SCHED __builtin_amdgcn_sched_barrier(0)
; template <class Epi, class Sched, bool ALIGN_EPI = false, bool SP2 = false>
; __device__ __forceinline__ void gemm_phase(PG8_LAS unsigned char* lds, const Gemm g, const Sched& S, const Epi& E) {
;     ...
;             PG8_LDB(B0, 1, 0); PG8_LDB(B1, 1, 1); PG8_SCHED; PG8_LDA(At, 1, 0); PG8_STAGE(PG8_SA(0, 1), a2 + hstep, voffA);
;             PG8_WAIT_V(8); PG8_WAIT_L(0); PG8_BAR; PG8_MMA(0, 0, At, B0); PG8_MMA(0, 1, At, B1); PG8_BAR; PG8_SCHED;
;             PG8_LDA(At, 1, 1); PG8_STAGE(PG8_SB(1, 0), b3, voffB); PG8_STAGE(PG8_SB(1, 1), b3 + hstep, voffB); PG8_STAGE(PG8_SA(1, 0), a3, voffA);
;             PG8_WAIT_V(8); PG8_WAIT_L(0); PG8_BAR; PG8_MMA(1, 0, At, B0); PG8_MMA(1, 1, At, B1); PG8_BAR; PG8_SCHED;
;     ...
;         if constexpr (ALIGN_EPI) { if (wr == 0) PG8_BAR; }
	s_add_i32 s55, 0, 0x18000
	v_add_u32_e32 v165, s55, v145
	s_add_i32 s56, 0, 0x1c000
	ds_read_b128 v[166:169], v165
	ds_read_b128 v[170:173], v165 offset:1024
	ds_read_b128 v[174:177], v165 offset:2048
	ds_read_b128 v[186:189], v165 offset:3072
	v_add_u32_e32 v165, s56, v145
	ds_read_b128 v[190:193], v165
	ds_read_b128 v[194:197], v165 offset:1024
	ds_read_b128 v[198:201], v165 offset:2048
	ds_read_b128 v[202:205], v165 offset:3072
	s_add_u32 s30, s30, 0x80000
	s_addc_u32 s31, s31, 0
	s_mov_b32 m0, s39
	ds_read_b128 v[206:209], v162 offset:32768
	ds_read_b128 v[210:213], v162 offset:33792
	ds_read_b128 v[214:217], v162 offset:34816
	ds_read_b128 v[218:221], v162 offset:35840
	ds_read_b128 v[222:225], v162 offset:36864
	ds_read_b128 v[226:229], v162 offset:37888
	ds_read_b128 v[230:233], v162 offset:38912
	ds_read_b128 v[234:237], v162 offset:39936
	global_load_lds_dwordx4 v150, s[30:31]
	s_mov_b32 m0, s40
	s_nop 0
	global_load_lds_dwordx4 v154, s[30:31]
	s_waitcnt vmcnt(8)
	s_waitcnt lgkmcnt(0)
	s_barrier
	s_setprio 1
	s_waitcnt lgkmcnt(0)
	v_mfma_f32_16x16x32_bf16 v[124:127], v[166:169], v[206:209], v[124:127]
	v_mfma_f32_16x16x32_bf16 v[124:127], v[170:173], v[210:213], v[124:127]
	v_mfma_f32_16x16x32_bf16 v[120:123], v[186:189], v[210:213], v[120:123]
	v_mfma_f32_16x16x32_bf16 v[120:123], v[174:177], v[206:209], v[120:123]
	v_mfma_f32_16x16x32_bf16 v[104:107], v[174:177], v[214:217], v[104:107]
	v_mfma_f32_16x16x32_bf16 v[104:107], v[186:189], v[218:221], v[104:107]
	v_mfma_f32_16x16x32_bf16 v[108:111], v[170:173], v[218:221], v[108:111]
	v_mfma_f32_16x16x32_bf16 v[108:111], v[166:169], v[214:217], v[108:111]
	v_mfma_f32_16x16x32_bf16 v[92:95], v[166:169], v[222:225], v[92:95]
	v_mfma_f32_16x16x32_bf16 v[92:95], v[170:173], v[226:229], v[92:95]
	v_mfma_f32_16x16x32_bf16 v[88:91], v[186:189], v[226:229], v[88:91]
	v_mfma_f32_16x16x32_bf16 v[88:91], v[174:177], v[222:225], v[88:91]
	v_mfma_f32_16x16x32_bf16 v[72:75], v[174:177], v[230:233], v[72:75]
	v_mfma_f32_16x16x32_bf16 v[72:75], v[186:189], v[234:237], v[72:75]
	v_mfma_f32_16x16x32_bf16 v[76:79], v[170:173], v[234:237], v[76:79]
	v_mfma_f32_16x16x32_bf16 v[76:79], v[166:169], v[230:233], v[76:79]
	s_setprio 0
	s_setprio 1
	v_mfma_f32_16x16x32_bf16 v[116:119], v[190:193], v[206:209], v[116:119]
	v_mfma_f32_16x16x32_bf16 v[116:119], v[194:197], v[210:213], v[116:119]
	v_mfma_f32_16x16x32_bf16 v[112:115], v[202:205], v[210:213], v[112:115]
	v_mfma_f32_16x16x32_bf16 v[112:115], v[198:201], v[206:209], v[112:115]
	v_mfma_f32_16x16x32_bf16 v[96:99], v[198:201], v[214:217], v[96:99]
	v_mfma_f32_16x16x32_bf16 v[96:99], v[202:205], v[218:221], v[96:99]
	v_mfma_f32_16x16x32_bf16 v[100:103], v[194:197], v[218:221], v[100:103]
	v_mfma_f32_16x16x32_bf16 v[100:103], v[190:193], v[214:217], v[100:103]
	v_mfma_f32_16x16x32_bf16 v[84:87], v[190:193], v[222:225], v[84:87]
	v_mfma_f32_16x16x32_bf16 v[84:87], v[194:197], v[226:229], v[84:87]
	v_mfma_f32_16x16x32_bf16 v[80:83], v[202:205], v[226:229], v[80:83]
	v_mfma_f32_16x16x32_bf16 v[80:83], v[198:201], v[222:225], v[80:83]
	v_mfma_f32_16x16x32_bf16 v[64:67], v[198:201], v[230:233], v[64:67]
	v_mfma_f32_16x16x32_bf16 v[64:67], v[202:205], v[234:237], v[64:67]
	v_mfma_f32_16x16x32_bf16 v[68:71], v[194:197], v[234:237], v[68:71]
	v_mfma_f32_16x16x32_bf16 v[68:71], v[190:193], v[230:233], v[68:71]
	s_setprio 0
	s_barrier
	s_add_i32 s30, s55, s36
	s_mov_b32 m0, s30
	ds_read_b128 v[206:209], v162 offset:49152
	ds_read_b128 v[210:213], v162 offset:50176
	ds_read_b128 v[214:217], v162 offset:51200
	ds_read_b128 v[218:221], v162 offset:52224
	ds_read_b128 v[222:225], v162 offset:53248
	ds_read_b128 v[226:229], v162 offset:54272
	ds_read_b128 v[230:233], v162 offset:55296
	ds_read_b128 v[234:237], v162 offset:56320
	global_load_lds_dwordx4 v152, s[98:99]
	s_add_i32 m0, s30, 0x2000
	s_add_u32 s28, s28, 0x80080
	s_addc_u32 s29, s29, 0
	s_add_i32 s30, s56, s36
	global_load_lds_dwordx4 v156, s[98:99]
	s_mov_b32 m0, s30
	s_nop 0
	global_load_lds_dwordx4 v152, s[28:29]
	s_add_i32 m0, s30, 0x2000
	s_nop 0
	global_load_lds_dwordx4 v156, s[28:29]
	s_mov_b32 m0, s42
	s_nop 0
	global_load_lds_dwordx4 v150, s[100:101]
	s_mov_b32 m0, s43
	s_nop 0
	global_load_lds_dwordx4 v154, s[100:101]
	s_waitcnt vmcnt(8)
	s_waitcnt lgkmcnt(0)
	s_barrier
	s_setprio 1
	s_waitcnt lgkmcnt(0)
	v_mfma_f32_16x16x32_bf16 v[60:63], v[166:169], v[206:209], v[60:63]
	v_mfma_f32_16x16x32_bf16 v[60:63], v[170:173], v[210:213], v[60:63]
	v_mfma_f32_16x16x32_bf16 v[56:59], v[186:189], v[210:213], v[56:59]
	v_mfma_f32_16x16x32_bf16 v[56:59], v[174:177], v[206:209], v[56:59]
	v_mfma_f32_16x16x32_bf16 v[40:43], v[174:177], v[214:217], v[40:43]
	v_mfma_f32_16x16x32_bf16 v[40:43], v[186:189], v[218:221], v[40:43]
	v_mfma_f32_16x16x32_bf16 v[44:47], v[170:173], v[218:221], v[44:47]
	v_mfma_f32_16x16x32_bf16 v[44:47], v[166:169], v[214:217], v[44:47]
	v_mfma_f32_16x16x32_bf16 v[28:31], v[166:169], v[222:225], v[28:31]
	v_mfma_f32_16x16x32_bf16 v[28:31], v[170:173], v[226:229], v[28:31]
	v_mfma_f32_16x16x32_bf16 v[24:27], v[186:189], v[226:229], v[24:27]
	v_mfma_f32_16x16x32_bf16 v[24:27], v[174:177], v[222:225], v[24:27]
	v_mfma_f32_16x16x32_bf16 v[8:11], v[174:177], v[230:233], v[8:11]
	v_mfma_f32_16x16x32_bf16 v[8:11], v[186:189], v[234:237], v[8:11]
	v_mfma_f32_16x16x32_bf16 v[12:15], v[170:173], v[234:237], v[12:15]
	v_mfma_f32_16x16x32_bf16 v[12:15], v[166:169], v[230:233], v[12:15]
	s_setprio 0
	s_setprio 1
	v_mfma_f32_16x16x32_bf16 v[52:55], v[190:193], v[206:209], v[52:55]
	v_mfma_f32_16x16x32_bf16 v[52:55], v[194:197], v[210:213], v[52:55]
	v_mfma_f32_16x16x32_bf16 v[48:51], v[202:205], v[210:213], v[48:51]
	v_mfma_f32_16x16x32_bf16 v[48:51], v[198:201], v[206:209], v[48:51]
	v_mfma_f32_16x16x32_bf16 v[32:35], v[198:201], v[214:217], v[32:35]
	v_mfma_f32_16x16x32_bf16 v[32:35], v[202:205], v[218:221], v[32:35]
	v_mfma_f32_16x16x32_bf16 v[36:39], v[194:197], v[218:221], v[36:39]
	v_mfma_f32_16x16x32_bf16 v[36:39], v[190:193], v[214:217], v[36:39]
	v_mfma_f32_16x16x32_bf16 v[20:23], v[190:193], v[222:225], v[20:23]
	v_mfma_f32_16x16x32_bf16 v[20:23], v[194:197], v[226:229], v[20:23]
	v_mfma_f32_16x16x32_bf16 v[16:19], v[202:205], v[226:229], v[16:19]
	v_mfma_f32_16x16x32_bf16 v[16:19], v[198:201], v[222:225], v[16:19]
	v_mfma_f32_16x16x32_bf16 v[0:3], v[198:201], v[230:233], v[0:3]
	v_mfma_f32_16x16x32_bf16 v[0:3], v[202:205], v[234:237], v[0:3]
	v_mfma_f32_16x16x32_bf16 v[4:7], v[194:197], v[234:237], v[4:7]
	v_mfma_f32_16x16x32_bf16 v[4:7], v[190:193], v[230:233], v[4:7]
	s_setprio 0
	s_barrier
	s_add_i32 s54, s54, 2
	s_add_u32 s26, s26, 0x100
	s_addc_u32 s27, s27, 0
	s_add_u32 s52, s52, 0x100
	s_addc_u32 s53, s53, 0
	s_cmp_gt_u32 s54, 29
	s_cbranch_scc0 .LBB0_1279
	s_and_b64 vcc, exec, s[16:17]
	s_cbranch_vccz .LBB0_1282
	s_barrier

; #define PG8_STAGE(bufoff, gbase, voff) do { _Pragma("unroll") for (int _i = 0; _i < 2; ++_i) \
;         __builtin_amdgcn_global_load_lds((const unsigned*)((const char*)(gbase) + (voff)[_i]), (PG8_LAS unsigned*)(lds + (bufoff) + ldsw + _i * 8192), 16, 0, 0); } while (0)
; #define PG8_LDA(dst, b, h) do { _Pragma("unroll") for (int m = 0; m < 4; ++m) _Pragma("unroll") for (int k = 0; k < 2; ++k) dst[m][k] = *(const PG8_LAS bf16x8*)(lds + PG8_SA(b, h) + aoff + m * 2048 + k * 1024); } while (0)
; #define PG8_LDB(dst, b, h) do { _Pragma("unroll") for (int n = 0; n < 2; ++n) _Pragma("unroll") for (int k = 0; k < 2; ++k) dst[n][k] = *(const PG8_LAS bf16x8*)(lds + PG8_SB(b, h) + boff + n * 2048 + k * 1024); } while (0)
; #define PG8_MMA(ai, bj, At, Bt) do { __builtin_amdgcn_s_setprio(1); _Pragma("unroll") for (int m = 0; m < 4; ++m) _Pragma("unroll") for (int n = 0; n < 2; ++n) _Pragma("unroll") for (int k = 0; k < 2; ++k) \
;         acc[ai][bj][m][n] = __builtin_amdgcn_mfma_f32_16x16x32_bf16(Bt[n][k], At[m][k], acc[ai][bj][m][n], 0, 0, 0); __builtin_amdgcn_s_setprio(0); } while (0)
; #define PG8_WAIT_V(n) asm volatile("s_waitcnt vmcnt(" #n ")" ::: "memory")
; #define PG8_BAR __builtin_amdgcn_s_barrier()
; template <class Epi, class Sched, bool ALIGN_EPI = false, bool SP2 = false>
; __device__ __forceinline__ void gemm_phase(PG8_LAS unsigned char* lds, const Gemm g, const Sched& S, const Epi& E) {
;     ...
;         for (int t = 0; t < nt; t += 2) {
;             const bool last = (t == nt - 2);
;             const char* a1 = cA + (size_t)(t + 1) * kstep;
;             const char* a2 = last ? nA : cA + (size_t)(t + 2) * kstep; const char* b2 = last ? nB : cB + (size_t)(t + 2) * kstep;
;             const char* a3 = a2 + kstep; const char* b3 = b2 + kstep;
;             if (last && has_next) S.a_ready(nxt);
;             if constexpr (SP2) {
;             PG8_LDB(B0, 0, 0); PG8_LDB(B1, 0, 1); PG8_SCHED; PG8_LDA(At, 0, 0); PG8_STAGE(PG8_SA(1, 1), a1 + hstep, voffA);
;             PG8_WAIT_V(8); PG8_WAIT_L(0); PG8_BAR; PG8_MMA(0, 0, At, B0); PG8_MMA(0, 1, At, B1); PG8_BAR; PG8_SCHED;
;             PG8_LDA(At, 0, 1); PG8_STAGE(PG8_SB(0, 0), b2, voffB); PG8_STAGE(PG8_SB(0, 1), b2 + hstep, voffB); PG8_STAGE(PG8_SA(0, 0), a2, voffA);
;             PG8_WAIT_V(8); PG8_WAIT_L(0); PG8_BAR; PG8_MMA(1, 0, At, B0); PG8_MMA(1, 1, At, B1); PG8_BAR; PG8_SCHED;
.LBB0_1361:
	ds_read_b128 v[128:131], v166
	ds_read_b128 v[132:135], v166 offset:1024
	ds_read_b128 v[160:163], v166 offset:2048
	ds_read_b128 v[170:173], v166 offset:3072
	ds_read_b128 v[174:177], v167
	ds_read_b128 v[186:189], v167 offset:1024
	ds_read_b128 v[190:193], v167 offset:2048
	ds_read_b128 v[194:197], v167 offset:3072
	s_add_u32 s22, s20, 0xffea0080
	s_addc_u32 s23, s21, -1
	s_cmpk_eq_i32 s55, 0x54
	s_cselect_b32 s25, s7, s23
	s_cselect_b32 s24, s6, s22
	s_cselect_b32 s23, s19, s54
	s_cselect_b32 s22, s18, s53
	s_add_i32 m0, s29, 0xc000
	ds_read_b128 v[198:201], v168
	ds_read_b128 v[202:205], v168 offset:1024
	ds_read_b128 v[206:209], v168 offset:2048
	ds_read_b128 v[210:213], v168 offset:3072
	ds_read_b128 v[214:217], v168 offset:4096
	ds_read_b128 v[218:221], v168 offset:5120
	ds_read_b128 v[222:225], v168 offset:6144
	ds_read_b128 v[226:229], v168 offset:7168
	global_load_lds_dwordx4 v150, s[20:21]
	s_add_i32 m0, s29, 0xe000
	s_nop 0
	global_load_lds_dwordx4 v152, s[20:21]
	s_waitcnt vmcnt(8)
	s_waitcnt lgkmcnt(0)
	s_barrier
	s_setprio 1
	s_waitcnt lgkmcnt(0)
	v_mfma_f32_16x16x32_bf16 v[124:127], v[128:131], v[198:201], v[124:127]
	v_mfma_f32_16x16x32_bf16 v[124:127], v[132:135], v[202:205], v[124:127]
	v_mfma_f32_16x16x32_bf16 v[120:123], v[170:173], v[202:205], v[120:123]
	v_mfma_f32_16x16x32_bf16 v[120:123], v[160:163], v[198:201], v[120:123]
	v_mfma_f32_16x16x32_bf16 v[104:107], v[160:163], v[206:209], v[104:107]
	v_mfma_f32_16x16x32_bf16 v[104:107], v[170:173], v[210:213], v[104:107]
	v_mfma_f32_16x16x32_bf16 v[108:111], v[132:135], v[210:213], v[108:111]
	v_mfma_f32_16x16x32_bf16 v[108:111], v[128:131], v[206:209], v[108:111]
	v_mfma_f32_16x16x32_bf16 v[92:95], v[128:131], v[214:217], v[92:95]
	v_mfma_f32_16x16x32_bf16 v[92:95], v[132:135], v[218:221], v[92:95]
	v_mfma_f32_16x16x32_bf16 v[88:91], v[170:173], v[218:221], v[88:91]
	v_mfma_f32_16x16x32_bf16 v[88:91], v[160:163], v[214:217], v[88:91]
	v_mfma_f32_16x16x32_bf16 v[72:75], v[160:163], v[222:225], v[72:75]
	v_mfma_f32_16x16x32_bf16 v[72:75], v[170:173], v[226:229], v[72:75]
	v_mfma_f32_16x16x32_bf16 v[76:79], v[132:135], v[226:229], v[76:79]
	v_mfma_f32_16x16x32_bf16 v[76:79], v[128:131], v[222:225], v[76:79]
	s_setprio 0
	s_setprio 1
	v_mfma_f32_16x16x32_bf16 v[116:119], v[174:177], v[198:201], v[116:119]
	v_mfma_f32_16x16x32_bf16 v[116:119], v[186:189], v[202:205], v[116:119]
	v_mfma_f32_16x16x32_bf16 v[112:115], v[194:197], v[202:205], v[112:115]
	v_mfma_f32_16x16x32_bf16 v[112:115], v[190:193], v[198:201], v[112:115]
	v_mfma_f32_16x16x32_bf16 v[96:99], v[190:193], v[206:209], v[96:99]
	v_mfma_f32_16x16x32_bf16 v[96:99], v[194:197], v[210:213], v[96:99]
	v_mfma_f32_16x16x32_bf16 v[100:103], v[186:189], v[210:213], v[100:103]
	v_mfma_f32_16x16x32_bf16 v[100:103], v[174:177], v[206:209], v[100:103]
	v_mfma_f32_16x16x32_bf16 v[84:87], v[174:177], v[214:217], v[84:87]
	v_mfma_f32_16x16x32_bf16 v[84:87], v[186:189], v[218:221], v[84:87]
	v_mfma_f32_16x16x32_bf16 v[80:83], v[194:197], v[218:221], v[80:83]
	v_mfma_f32_16x16x32_bf16 v[80:83], v[190:193], v[214:217], v[80:83]
	v_mfma_f32_16x16x32_bf16 v[64:67], v[190:193], v[222:225], v[64:67]
	v_mfma_f32_16x16x32_bf16 v[64:67], v[194:197], v[226:229], v[64:67]
	v_mfma_f32_16x16x32_bf16 v[68:71], v[186:189], v[226:229], v[68:71]
	v_mfma_f32_16x16x32_bf16 v[68:71], v[174:177], v[222:225], v[68:71]
	s_setprio 0
	s_barrier
	s_add_u32 s98, s22, 0x80
	s_addc_u32 s99, s23, 0
	s_add_u32 s100, s24, 0x80
	s_addc_u32 s101, s25, 0
	s_add_i32 s56, s43, s28
	s_mov_b32 m0, s56
	ds_read_b128 v[198:201], v168 offset:16384
	ds_read_b128 v[202:205], v168 offset:17408
	ds_read_b128 v[206:209], v168 offset:18432
	ds_read_b128 v[210:213], v168 offset:19456
	ds_read_b128 v[214:217], v168 offset:20480
	ds_read_b128 v[218:221], v168 offset:21504
	ds_read_b128 v[222:225], v168 offset:22528
	ds_read_b128 v[226:229], v168 offset:23552
	global_load_lds_dwordx4 v144, s[22:23]
	s_add_i32 m0, s56, 0x2000
	s_add_u32 s56, s22, 0x160000
	s_addc_u32 s57, s23, 0
	s_add_i32 s58, s44, s28
	global_load_lds_dwordx4 v148, s[22:23]
	s_mov_b32 m0, s58
	s_nop 0
	global_load_lds_dwordx4 v144, s[56:57]
	s_add_i32 m0, s58, 0x2000
	s_nop 0
	global_load_lds_dwordx4 v148, s[56:57]
	s_mov_b32 m0, s29
	s_nop 0
	global_load_lds_dwordx4 v142, s[24:25]
	s_mov_b32 m0, s30
	s_nop 0
	global_load_lds_dwordx4 v146, s[24:25]
	s_waitcnt vmcnt(8)
	s_waitcnt lgkmcnt(0)
	s_barrier
	s_setprio 1
	s_waitcnt lgkmcnt(0)
	v_mfma_f32_16x16x32_bf16 v[60:63], v[128:131], v[198:201], v[60:63]
	v_mfma_f32_16x16x32_bf16 v[60:63], v[132:135], v[202:205], v[60:63]
	v_mfma_f32_16x16x32_bf16 v[56:59], v[170:173], v[202:205], v[56:59]
	v_mfma_f32_16x16x32_bf16 v[56:59], v[160:163], v[198:201], v[56:59]
	v_mfma_f32_16x16x32_bf16 v[40:43], v[160:163], v[206:209], v[40:43]
	v_mfma_f32_16x16x32_bf16 v[40:43], v[170:173], v[210:213], v[40:43]
	v_mfma_f32_16x16x32_bf16 v[44:47], v[132:135], v[210:213], v[44:47]
	v_mfma_f32_16x16x32_bf16 v[44:47], v[128:131], v[206:209], v[44:47]
	v_mfma_f32_16x16x32_bf16 v[28:31], v[128:131], v[214:217], v[28:31]
	v_mfma_f32_16x16x32_bf16 v[28:31], v[132:135], v[218:221], v[28:31]
	v_mfma_f32_16x16x32_bf16 v[24:27], v[170:173], v[218:221], v[24:27]
	v_mfma_f32_16x16x32_bf16 v[24:27], v[160:163], v[214:217], v[24:27]
	v_mfma_f32_16x16x32_bf16 v[8:11], v[160:163], v[222:225], v[8:11]
	v_mfma_f32_16x16x32_bf16 v[8:11], v[170:173], v[226:229], v[8:11]
	v_mfma_f32_16x16x32_bf16 v[12:15], v[132:135], v[226:229], v[12:15]
	v_mfma_f32_16x16x32_bf16 v[12:15], v[128:131], v[222:225], v[12:15]
	s_setprio 0
	s_setprio 1
	v_mfma_f32_16x16x32_bf16 v[52:55], v[174:177], v[198:201], v[52:55]
	v_mfma_f32_16x16x32_bf16 v[52:55], v[186:189], v[202:205], v[52:55]
	v_mfma_f32_16x16x32_bf16 v[48:51], v[194:197], v[202:205], v[48:51]
	v_mfma_f32_16x16x32_bf16 v[48:51], v[190:193], v[198:201], v[48:51]
	v_mfma_f32_16x16x32_bf16 v[32:35], v[190:193], v[206:209], v[32:35]
	v_mfma_f32_16x16x32_bf16 v[32:35], v[194:197], v[210:213], v[32:35]
	v_mfma_f32_16x16x32_bf16 v[36:39], v[186:189], v[210:213], v[36:39]
	v_mfma_f32_16x16x32_bf16 v[36:39], v[174:177], v[206:209], v[36:39]
	v_mfma_f32_16x16x32_bf16 v[20:23], v[174:177], v[214:217], v[20:23]
	v_mfma_f32_16x16x32_bf16 v[20:23], v[186:189], v[218:221], v[20:23]
	v_mfma_f32_16x16x32_bf16 v[16:19], v[194:197], v[218:221], v[16:19]
	v_mfma_f32_16x16x32_bf16 v[16:19], v[190:193], v[214:217], v[16:19]
	v_mfma_f32_16x16x32_bf16 v[0:3], v[190:193], v[222:225], v[0:3]
	v_mfma_f32_16x16x32_bf16 v[0:3], v[194:197], v[226:229], v[0:3]
	v_mfma_f32_16x16x32_bf16 v[4:7], v[186:189], v[226:229], v[4:7]
	v_mfma_f32_16x16x32_bf16 v[4:7], v[174:177], v[222:225], v[4:7]
	s_setprio 0
	s_barrier
; #define PG8_STAGE(bufoff, gbase, voff) do { _Pragma("unroll") for (int _i = 0; _i < 2; ++_i) \
;         __builtin_amdgcn_global_load_lds((const unsigned*)((const char*)(gbase) + (voff)[_i]), (PG8_LAS unsigned*)(lds + (bufoff) + ldsw + _i * 8192), 16, 0, 0); } while (0)
; #define PG8_LDA(dst, b, h) do { _Pragma("unroll") for (int m = 0; m < 4; ++m) _Pragma("unroll") for (int k = 0; k < 2; ++k) dst[m][k] = *(const PG8_LAS bf16x8*)(lds + PG8_SA(b, h) + aoff + m * 2048 + k * 1024); } while (0)
; #define PG8_LDB(dst, b, h) do { _Pragma("unroll") for (int n = 0; n < 2; ++n) _Pragma("unroll") for (int k = 0; k < 2; ++k) dst[n][k] = *(const PG8_LAS bf16x8*)(lds + PG8_SB(b, h) + boff + n * 2048 + k * 1024); } while (0)
; #define PG8_MMA(ai, bj, At, Bt) do { __builtin_amdgcn_s_setprio(1); _Pragma("unroll") for (int m = 0; m < 4; ++m) _Pragma("unroll") for (int n = 0; n < 2; ++n) _Pragma("unroll") for (int k = 0; k < 2; ++k) \
;         acc[ai][bj][m][n] = __builtin_amdgcn_mfma_f32_16x16x32_bf16(Bt[n][k], At[m][k], acc[ai][bj][m][n], 0, 0, 0); __builtin_amdgcn_s_setprio(0); } while (0)
; #define PG8_WAIT_V(n) asm volatile("s_waitcnt vmcnt(" #n ")" ::: "memory")
; #define PG8_WAIT_L(n) asm volatile("s_waitcnt lgkmcnt(" #n ")" ::: "memory")
; #define PG8_BAR __builtin_amdgcn_s_barrier()
; #define PG8_SCHED __builtin_amdgcn_sched_barrier(0)
; template <class Epi, class Sched, bool ALIGN_EPI = false, bool SP2 = false>
; __device__ __forceinline__ void gemm_phase(PG8_LAS unsigned char* lds, const Gemm g, const Sched& S, const Epi& E) {
;     ...
;             PG8_LDB(B0, 1, 0); PG8_LDB(B1, 1, 1); PG8_SCHED; PG8_LDA(At, 1, 0); PG8_STAGE(PG8_SA(0, 1), a2 + hstep, voffA);
;             PG8_WAIT_V(8); PG8_WAIT_L(0); PG8_BAR; PG8_MMA(0, 0, At, B0); PG8_MMA(0, 1, At, B1); PG8_BAR; PG8_SCHED;
;             PG8_LDA(At, 1, 1); PG8_STAGE(PG8_SB(1, 0), b3, voffB); PG8_STAGE(PG8_SB(1, 1), b3 + hstep, voffB); PG8_STAGE(PG8_SA(1, 0), a3, voffA);
;             PG8_WAIT_V(8); PG8_WAIT_L(0); PG8_BAR; PG8_MMA(1, 0, At, B0); PG8_MMA(1, 1, At, B1); PG8_BAR; PG8_SCHED;
;     ...
;         if constexpr (ALIGN_EPI) { if (wr == 0) PG8_BAR; }
	s_add_i32 s56, 0, 0x18000
	v_add_u32_e32 v169, s56, v164
	s_add_i32 s57, 0, 0x1c000
	ds_read_b128 v[128:131], v169
	ds_read_b128 v[132:135], v169 offset:1024
	ds_read_b128 v[160:163], v169 offset:2048
	ds_read_b128 v[170:173], v169 offset:3072
	v_add_u32_e32 v169, s57, v164
	ds_read_b128 v[174:177], v169
	ds_read_b128 v[186:189], v169 offset:1024
	ds_read_b128 v[190:193], v169 offset:2048
	ds_read_b128 v[194:197], v169 offset:3072
	s_add_u32 s24, s24, 0x160000
	s_addc_u32 s25, s25, 0
	s_mov_b32 m0, s31
	ds_read_b128 v[198:201], v168 offset:32768
	ds_read_b128 v[202:205], v168 offset:33792
	ds_read_b128 v[206:209], v168 offset:34816
	ds_read_b128 v[210:213], v168 offset:35840
	ds_read_b128 v[214:217], v168 offset:36864
	ds_read_b128 v[218:221], v168 offset:37888
	ds_read_b128 v[222:225], v168 offset:38912
	ds_read_b128 v[226:229], v168 offset:39936
	global_load_lds_dwordx4 v142, s[24:25]
	s_mov_b32 m0, s33
	s_nop 0
	global_load_lds_dwordx4 v146, s[24:25]
	s_waitcnt vmcnt(8)
	s_waitcnt lgkmcnt(0)
	s_barrier
	s_setprio 1
	s_waitcnt lgkmcnt(0)
	v_mfma_f32_16x16x32_bf16 v[124:127], v[128:131], v[198:201], v[124:127]
	v_mfma_f32_16x16x32_bf16 v[124:127], v[132:135], v[202:205], v[124:127]
	v_mfma_f32_16x16x32_bf16 v[120:123], v[170:173], v[202:205], v[120:123]
	v_mfma_f32_16x16x32_bf16 v[120:123], v[160:163], v[198:201], v[120:123]
	v_mfma_f32_16x16x32_bf16 v[104:107], v[160:163], v[206:209], v[104:107]
	v_mfma_f32_16x16x32_bf16 v[104:107], v[170:173], v[210:213], v[104:107]
	v_mfma_f32_16x16x32_bf16 v[108:111], v[132:135], v[210:213], v[108:111]
	v_mfma_f32_16x16x32_bf16 v[108:111], v[128:131], v[206:209], v[108:111]
	v_mfma_f32_16x16x32_bf16 v[92:95], v[128:131], v[214:217], v[92:95]
	v_mfma_f32_16x16x32_bf16 v[92:95], v[132:135], v[218:221], v[92:95]
	v_mfma_f32_16x16x32_bf16 v[88:91], v[170:173], v[218:221], v[88:91]
	v_mfma_f32_16x16x32_bf16 v[88:91], v[160:163], v[214:217], v[88:91]
	v_mfma_f32_16x16x32_bf16 v[72:75], v[160:163], v[222:225], v[72:75]
	v_mfma_f32_16x16x32_bf16 v[72:75], v[170:173], v[226:229], v[72:75]
	v_mfma_f32_16x16x32_bf16 v[76:79], v[132:135], v[226:229], v[76:79]
	v_mfma_f32_16x16x32_bf16 v[76:79], v[128:131], v[222:225], v[76:79]
	s_setprio 0
	s_setprio 1
	v_mfma_f32_16x16x32_bf16 v[116:119], v[174:177], v[198:201], v[116:119]
	v_mfma_f32_16x16x32_bf16 v[116:119], v[186:189], v[202:205], v[116:119]
	v_mfma_f32_16x16x32_bf16 v[112:115], v[194:197], v[202:205], v[112:115]
	v_mfma_f32_16x16x32_bf16 v[112:115], v[190:193], v[198:201], v[112:115]
	v_mfma_f32_16x16x32_bf16 v[96:99], v[190:193], v[206:209], v[96:99]
	v_mfma_f32_16x16x32_bf16 v[96:99], v[194:197], v[210:213], v[96:99]
	v_mfma_f32_16x16x32_bf16 v[100:103], v[186:189], v[210:213], v[100:103]
	v_mfma_f32_16x16x32_bf16 v[100:103], v[174:177], v[206:209], v[100:103]
	v_mfma_f32_16x16x32_bf16 v[84:87], v[174:177], v[214:217], v[84:87]
	v_mfma_f32_16x16x32_bf16 v[84:87], v[186:189], v[218:221], v[84:87]
	v_mfma_f32_16x16x32_bf16 v[80:83], v[194:197], v[218:221], v[80:83]
	v_mfma_f32_16x16x32_bf16 v[80:83], v[190:193], v[214:217], v[80:83]
	v_mfma_f32_16x16x32_bf16 v[64:67], v[190:193], v[222:225], v[64:67]
	v_mfma_f32_16x16x32_bf16 v[64:67], v[194:197], v[226:229], v[64:67]
	v_mfma_f32_16x16x32_bf16 v[68:71], v[186:189], v[226:229], v[68:71]
	v_mfma_f32_16x16x32_bf16 v[68:71], v[174:177], v[222:225], v[68:71]
	s_setprio 0
	s_barrier
	s_add_i32 s24, s56, s28
	s_mov_b32 m0, s24
	ds_read_b128 v[198:201], v168 offset:49152
	ds_read_b128 v[202:205], v168 offset:50176
	ds_read_b128 v[206:209], v168 offset:51200
	ds_read_b128 v[210:213], v168 offset:52224
	ds_read_b128 v[214:217], v168 offset:53248
	ds_read_b128 v[218:221], v168 offset:54272
	ds_read_b128 v[222:225], v168 offset:55296
	ds_read_b128 v[226:229], v168 offset:56320
	global_load_lds_dwordx4 v144, s[98:99]
	s_add_i32 m0, s24, 0x2000
	s_add_u32 s22, s22, 0x160080
	s_addc_u32 s23, s23, 0
	s_add_i32 s24, s57, s28
	global_load_lds_dwordx4 v148, s[98:99]
	s_mov_b32 m0, s24
	s_nop 0
	global_load_lds_dwordx4 v144, s[22:23]
	s_add_i32 m0, s24, 0x2000
	s_nop 0
	global_load_lds_dwordx4 v148, s[22:23]
	s_mov_b32 m0, s38
	s_nop 0
	global_load_lds_dwordx4 v142, s[100:101]
	s_mov_b32 m0, s39
	s_nop 0
	global_load_lds_dwordx4 v146, s[100:101]
	s_waitcnt vmcnt(8)
	s_waitcnt lgkmcnt(0)
	s_barrier
	s_setprio 1
	s_waitcnt lgkmcnt(0)
	v_mfma_f32_16x16x32_bf16 v[60:63], v[128:131], v[198:201], v[60:63]
	v_mfma_f32_16x16x32_bf16 v[60:63], v[132:135], v[202:205], v[60:63]
	v_mfma_f32_16x16x32_bf16 v[56:59], v[170:173], v[202:205], v[56:59]
	v_mfma_f32_16x16x32_bf16 v[56:59], v[160:163], v[198:201], v[56:59]
	v_mfma_f32_16x16x32_bf16 v[40:43], v[160:163], v[206:209], v[40:43]
	v_mfma_f32_16x16x32_bf16 v[40:43], v[170:173], v[210:213], v[40:43]
	v_mfma_f32_16x16x32_bf16 v[44:47], v[132:135], v[210:213], v[44:47]
	v_mfma_f32_16x16x32_bf16 v[44:47], v[128:131], v[206:209], v[44:47]
	v_mfma_f32_16x16x32_bf16 v[28:31], v[128:131], v[214:217], v[28:31]
	v_mfma_f32_16x16x32_bf16 v[28:31], v[132:135], v[218:221], v[28:31]
	v_mfma_f32_16x16x32_bf16 v[24:27], v[170:173], v[218:221], v[24:27]
	v_mfma_f32_16x16x32_bf16 v[24:27], v[160:163], v[214:217], v[24:27]
	v_mfma_f32_16x16x32_bf16 v[8:11], v[160:163], v[222:225], v[8:11]
	v_mfma_f32_16x16x32_bf16 v[8:11], v[170:173], v[226:229], v[8:11]
	v_mfma_f32_16x16x32_bf16 v[12:15], v[132:135], v[226:229], v[12:15]
	v_mfma_f32_16x16x32_bf16 v[12:15], v[128:131], v[222:225], v[12:15]
	s_setprio 0
	s_setprio 1
	v_mfma_f32_16x16x32_bf16 v[52:55], v[174:177], v[198:201], v[52:55]
	v_mfma_f32_16x16x32_bf16 v[52:55], v[186:189], v[202:205], v[52:55]
	v_mfma_f32_16x16x32_bf16 v[48:51], v[194:197], v[202:205], v[48:51]
	v_mfma_f32_16x16x32_bf16 v[48:51], v[190:193], v[198:201], v[48:51]
	v_mfma_f32_16x16x32_bf16 v[32:35], v[190:193], v[206:209], v[32:35]
	v_mfma_f32_16x16x32_bf16 v[32:35], v[194:197], v[210:213], v[32:35]
	v_mfma_f32_16x16x32_bf16 v[36:39], v[186:189], v[210:213], v[36:39]
	v_mfma_f32_16x16x32_bf16 v[36:39], v[174:177], v[206:209], v[36:39]
	v_mfma_f32_16x16x32_bf16 v[20:23], v[174:177], v[214:217], v[20:23]
	v_mfma_f32_16x16x32_bf16 v[20:23], v[186:189], v[218:221], v[20:23]
	v_mfma_f32_16x16x32_bf16 v[16:19], v[194:197], v[218:221], v[16:19]
	v_mfma_f32_16x16x32_bf16 v[16:19], v[190:193], v[214:217], v[16:19]
	v_mfma_f32_16x16x32_bf16 v[0:3], v[190:193], v[222:225], v[0:3]
	v_mfma_f32_16x16x32_bf16 v[0:3], v[194:197], v[226:229], v[0:3]
	v_mfma_f32_16x16x32_bf16 v[4:7], v[186:189], v[226:229], v[4:7]
	v_mfma_f32_16x16x32_bf16 v[4:7], v[174:177], v[222:225], v[4:7]
	s_setprio 0
	s_barrier
	s_add_i32 s55, s55, 2
	s_add_u32 s20, s20, 0x100
	s_addc_u32 s21, s21, 0
	s_add_u32 s53, s53, 0x100
	s_addc_u32 s54, s54, 0
	s_cmpk_gt_u32 s55, 0x55
	s_cbranch_scc0 .LBB0_1361
	s_and_b64 vcc, exec, s[16:17]
	s_cbranch_vccz .LBB0_1364
	s_barrier

; __global__ void __launch_bounds__(NTHREADS, 2) mega_fwd(Args a_unused) {
	.amdhsa_kernel _Z8mega_fwd4Args
		.amdhsa_group_segment_fixed_size 0
		.amdhsa_private_segment_fixed_size 0
		.amdhsa_kernarg_size 448
		.amdhsa_user_sgpr_count 2
		.amdhsa_user_sgpr_dispatch_ptr 0
		.amdhsa_user_sgpr_queue_ptr 0
		.amdhsa_user_sgpr_kernarg_segment_ptr 1
		.amdhsa_user_sgpr_dispatch_id 0
		.amdhsa_user_sgpr_kernarg_preload_length 0
		.amdhsa_user_sgpr_kernarg_preload_offset 0
		.amdhsa_user_sgpr_private_segment_size 0
		.amdhsa_uses_dynamic_stack 0
		.amdhsa_enable_private_segment 0
		.amdhsa_system_sgpr_workgroup_id_x 1
		.amdhsa_system_sgpr_workgroup_id_y 0
		.amdhsa_system_sgpr_workgroup_id_z 0
		.amdhsa_system_sgpr_workgroup_info 0
		.amdhsa_system_vgpr_workitem_id 2
		.amdhsa_next_free_vgpr 256
		.amdhsa_next_free_sgpr 102
		.amdhsa_accum_offset 256
		.amdhsa_reserve_vcc 1
		.amdhsa_float_round_mode_32 0
		.amdhsa_float_round_mode_16_64 0
		.amdhsa_float_denorm_mode_32 3
		.amdhsa_float_denorm_mode_16_64 3
		.amdhsa_dx10_clamp 1
		.amdhsa_ieee_mode 1
		.amdhsa_fp16_overflow 0
		.amdhsa_tg_split 0
		.amdhsa_exception_fp_ieee_invalid_op 0
		.amdhsa_exception_fp_denorm_src 0
		.amdhsa_exception_fp_ieee_div_zero 0
		.amdhsa_exception_fp_ieee_overflow 0
		.amdhsa_exception_fp_ieee_underflow 0
		.amdhsa_exception_fp_ieee_inexact 0
		.amdhsa_exception_int_div_zero 0
	.end_amdhsa_kernel

; __global__ void __launch_bounds__(NTHREADS, 2) mega_fwd(Args a_unused) {
amdhsa.kernels:
  - .agpr_count:     0
    .args:
      - .offset:         0
        .size:           192
        .value_kind:     by_value
      - .offset:         192
        .size:           4
        .value_kind:     hidden_block_count_x
      - .offset:         196
        .size:           4
        .value_kind:     hidden_block_count_y
      - .offset:         200
        .size:           4
        .value_kind:     hidden_block_count_z
      - .offset:         204
        .size:           2
        .value_kind:     hidden_group_size_x
      - .offset:         206
        .size:           2
        .value_kind:     hidden_group_size_y
      - .offset:         208
        .size:           2
        .value_kind:     hidden_group_size_z
      - .offset:         210
        .size:           2
        .value_kind:     hidden_remainder_x
      - .offset:         212
        .size:           2
        .value_kind:     hidden_remainder_y
      - .offset:         214
        .size:           2
        .value_kind:     hidden_remainder_z
      - .offset:         232
        .size:           8
        .value_kind:     hidden_global_offset_x
      - .offset:         240
        .size:           8
        .value_kind:     hidden_global_offset_y
      - .offset:         248
        .size:           8
        .value_kind:     hidden_global_offset_z
      - .offset:         256
        .size:           2
        .value_kind:     hidden_grid_dims
      - .offset:         280
        .size:           8
        .value_kind:     hidden_multigrid_sync_arg
      - .offset:         312
        .size:           4
        .value_kind:     hidden_dynamic_lds_size
    .group_segment_fixed_size: 0
    .kernarg_segment_align: 8
    .kernarg_segment_size: 448
    .language:       OpenCL C
    .language_version:
      - 2
      - 0
    .max_flat_workgroup_size: 512
    .name:           _Z8mega_fwd4Args
    .private_segment_fixed_size: 0
    .sgpr_count:     108
    .sgpr_spill_count: 46
    .symbol:         _Z8mega_fwd4Args.kd
    .uniform_work_group_size: 1
    .uses_dynamic_stack: false
    .vgpr_count:     256
    .vgpr_spill_count: 0
    .wavefront_size: 64
